# all five live GEMM K loops: LDS-DMA source = scalar base pair + 32-bit lane offset (16 fewer 64-bit VALU adds per iteration)
# speedup vs baseline: 1.0110x; 1.0059x over previous
.LBB0_163:
	ds_read_b128 v[152:155], v149
	ds_read_b128 v[156:159], v149 offset:1024
	ds_read_b128 v[160:163], v149 offset:2048
	ds_read_b128 v[164:167], v149 offset:3072
	ds_read_b128 v[168:171], v150
	ds_read_b128 v[172:175], v150 offset:1024
	ds_read_b128 v[176:179], v150 offset:2048
	ds_read_b128 v[180:183], v150 offset:3072
	s_add_u32 s24, s22, 0xfff80080
	s_addc_u32 s25, s23, -1
	s_cmp_eq_u32 s58, 28
	s_cselect_b32 s27, s15, s25
	s_cselect_b32 s26, s54, s24
	s_cselect_b32 s25, s13, s57
	s_cselect_b32 s24, s55, s56
	s_add_u32 s98, s24, s6
	s_addc_u32 s99, s25, s7
	s_add_u32 s100, s26, s6
	s_addc_u32 s101, s27, s7
	s_add_i32 m0, s21, 0xc000
	ds_read_b128 v[184:187], v151
	ds_read_b128 v[188:191], v151 offset:1024
	ds_read_b128 v[192:195], v151 offset:2048
	ds_read_b128 v[196:199], v151 offset:3072
	ds_read_b128 v[200:203], v151 offset:4096
	ds_read_b128 v[204:207], v151 offset:5120
	ds_read_b128 v[208:211], v151 offset:6144
	ds_read_b128 v[212:215], v151 offset:7168
	global_load_lds_dwordx4 v136, s[22:23]
	s_add_i32 m0, s21, 0xe000
	s_nop 0
	global_load_lds_dwordx4 v138, s[22:23]
	s_waitcnt vmcnt(8)
	s_waitcnt lgkmcnt(0)
	s_barrier
	s_setprio 1
	s_waitcnt lgkmcnt(0)
	v_mfma_f32_16x16x32_bf16 v[124:127], v[152:155], v[184:187], v[124:127]
	v_mfma_f32_16x16x32_bf16 v[120:123], v[160:163], v[184:187], v[120:123]
	v_mfma_f32_16x16x32_bf16 v[116:119], v[152:155], v[192:195], v[116:119]
	v_mfma_f32_16x16x32_bf16 v[108:111], v[160:163], v[192:195], v[108:111]
	v_mfma_f32_16x16x32_bf16 v[100:103], v[152:155], v[200:203], v[100:103]
	v_mfma_f32_16x16x32_bf16 v[92:95], v[160:163], v[200:203], v[92:95]
	v_mfma_f32_16x16x32_bf16 v[84:87], v[152:155], v[208:211], v[84:87]
	v_mfma_f32_16x16x32_bf16 v[76:79], v[160:163], v[208:211], v[76:79]
	v_mfma_f32_16x16x32_bf16 v[124:127], v[156:159], v[188:191], v[124:127]
	v_mfma_f32_16x16x32_bf16 v[120:123], v[164:167], v[188:191], v[120:123]
	v_mfma_f32_16x16x32_bf16 v[116:119], v[156:159], v[196:199], v[116:119]
	v_mfma_f32_16x16x32_bf16 v[108:111], v[164:167], v[196:199], v[108:111]
	v_mfma_f32_16x16x32_bf16 v[100:103], v[156:159], v[204:207], v[100:103]
	v_mfma_f32_16x16x32_bf16 v[92:95], v[164:167], v[204:207], v[92:95]
	v_mfma_f32_16x16x32_bf16 v[84:87], v[156:159], v[212:215], v[84:87]
	v_mfma_f32_16x16x32_bf16 v[76:79], v[164:167], v[212:215], v[76:79]
	s_setprio 0
	s_setprio 1
	v_mfma_f32_16x16x32_bf16 v[112:115], v[168:171], v[184:187], v[112:115]
	v_mfma_f32_16x16x32_bf16 v[104:107], v[176:179], v[184:187], v[104:107]
	v_mfma_f32_16x16x32_bf16 v[96:99], v[168:171], v[192:195], v[96:99]
	v_mfma_f32_16x16x32_bf16 v[88:91], v[176:179], v[192:195], v[88:91]
	v_mfma_f32_16x16x32_bf16 v[80:83], v[168:171], v[200:203], v[80:83]
	v_mfma_f32_16x16x32_bf16 v[72:75], v[176:179], v[200:203], v[72:75]
	v_mfma_f32_16x16x32_bf16 v[68:71], v[168:171], v[208:211], v[68:71]
	v_mfma_f32_16x16x32_bf16 v[64:67], v[176:179], v[208:211], v[64:67]
	v_mfma_f32_16x16x32_bf16 v[112:115], v[172:175], v[188:191], v[112:115]
	v_mfma_f32_16x16x32_bf16 v[104:107], v[180:183], v[188:191], v[104:107]
	v_mfma_f32_16x16x32_bf16 v[96:99], v[172:175], v[196:199], v[96:99]
	v_mfma_f32_16x16x32_bf16 v[88:91], v[180:183], v[196:199], v[88:91]
	v_mfma_f32_16x16x32_bf16 v[80:83], v[172:175], v[204:207], v[80:83]
	v_mfma_f32_16x16x32_bf16 v[72:75], v[180:183], v[204:207], v[72:75]
	v_mfma_f32_16x16x32_bf16 v[68:71], v[172:175], v[212:215], v[68:71]
	v_mfma_f32_16x16x32_bf16 v[64:67], v[180:183], v[212:215], v[64:67]
	s_setprio 0
	s_barrier
	s_add_i32 s59, s43, s28
	s_mov_b32 m0, s59
	ds_read_b128 v[184:187], v151 offset:16384
	ds_read_b128 v[188:191], v151 offset:17408
	ds_read_b128 v[192:195], v151 offset:18432
	ds_read_b128 v[196:199], v151 offset:19456
	ds_read_b128 v[200:203], v151 offset:20480
	ds_read_b128 v[204:207], v151 offset:21504
	ds_read_b128 v[208:211], v151 offset:22528
	ds_read_b128 v[212:215], v151 offset:23552
	global_load_lds_dwordx4 v130, s[24:25]
	s_add_i32 m0, s59, 0x2000
	s_add_u32 s62, s24, 0x200000
	s_addc_u32 s63, s25, 0
	s_add_i32 s59, s48, s28
	global_load_lds_dwordx4 v134, s[24:25]
	s_mov_b32 m0, s59
	s_nop 0
	global_load_lds_dwordx4 v130, s[62:63]
	s_add_i32 m0, s59, 0x2000
	s_nop 0
	global_load_lds_dwordx4 v134, s[62:63]
	s_mov_b32 m0, s21
	s_nop 0
	global_load_lds_dwordx4 v128, s[26:27]
	s_mov_b32 m0, s31
	s_nop 0
	global_load_lds_dwordx4 v132, s[26:27]
	s_waitcnt vmcnt(8)
	s_waitcnt lgkmcnt(0)
	s_barrier
	s_setprio 1
	s_waitcnt lgkmcnt(0)
	v_mfma_f32_16x16x32_bf16 v[60:63], v[152:155], v[184:187], v[60:63]
	v_mfma_f32_16x16x32_bf16 v[56:59], v[160:163], v[184:187], v[56:59]
	v_mfma_f32_16x16x32_bf16 v[52:55], v[152:155], v[192:195], v[52:55]
	v_mfma_f32_16x16x32_bf16 v[44:47], v[160:163], v[192:195], v[44:47]
	v_mfma_f32_16x16x32_bf16 v[36:39], v[152:155], v[200:203], v[36:39]
	v_mfma_f32_16x16x32_bf16 v[28:31], v[160:163], v[200:203], v[28:31]
	v_mfma_f32_16x16x32_bf16 v[20:23], v[152:155], v[208:211], v[20:23]
	v_mfma_f32_16x16x32_bf16 v[12:15], v[160:163], v[208:211], v[12:15]
	v_mfma_f32_16x16x32_bf16 v[60:63], v[156:159], v[188:191], v[60:63]
	v_mfma_f32_16x16x32_bf16 v[56:59], v[164:167], v[188:191], v[56:59]
	v_mfma_f32_16x16x32_bf16 v[52:55], v[156:159], v[196:199], v[52:55]
	v_mfma_f32_16x16x32_bf16 v[44:47], v[164:167], v[196:199], v[44:47]
	v_mfma_f32_16x16x32_bf16 v[36:39], v[156:159], v[204:207], v[36:39]
	v_mfma_f32_16x16x32_bf16 v[28:31], v[164:167], v[204:207], v[28:31]
	v_mfma_f32_16x16x32_bf16 v[20:23], v[156:159], v[212:215], v[20:23]
	v_mfma_f32_16x16x32_bf16 v[12:15], v[164:167], v[212:215], v[12:15]
	s_setprio 0
	s_setprio 1
	v_mfma_f32_16x16x32_bf16 v[48:51], v[168:171], v[184:187], v[48:51]
	v_mfma_f32_16x16x32_bf16 v[40:43], v[176:179], v[184:187], v[40:43]
	v_mfma_f32_16x16x32_bf16 v[32:35], v[168:171], v[192:195], v[32:35]
	v_mfma_f32_16x16x32_bf16 v[24:27], v[176:179], v[192:195], v[24:27]
	v_mfma_f32_16x16x32_bf16 v[16:19], v[168:171], v[200:203], v[16:19]
	v_mfma_f32_16x16x32_bf16 v[8:11], v[176:179], v[200:203], v[8:11]
	v_mfma_f32_16x16x32_bf16 v[4:7], v[168:171], v[208:211], v[4:7]
	v_mfma_f32_16x16x32_bf16 v[0:3], v[176:179], v[208:211], v[0:3]
	v_mfma_f32_16x16x32_bf16 v[48:51], v[172:175], v[188:191], v[48:51]
	v_mfma_f32_16x16x32_bf16 v[40:43], v[180:183], v[188:191], v[40:43]
	v_mfma_f32_16x16x32_bf16 v[32:35], v[172:175], v[196:199], v[32:35]
	v_mfma_f32_16x16x32_bf16 v[24:27], v[180:183], v[196:199], v[24:27]
	v_mfma_f32_16x16x32_bf16 v[16:19], v[172:175], v[204:207], v[16:19]
	v_mfma_f32_16x16x32_bf16 v[8:11], v[180:183], v[204:207], v[8:11]
	v_mfma_f32_16x16x32_bf16 v[4:7], v[172:175], v[212:215], v[4:7]
	v_mfma_f32_16x16x32_bf16 v[0:3], v[180:183], v[212:215], v[0:3]
	s_setprio 0
	s_barrier
	s_add_i32 s59, 0, 0x18000
	s_add_i32 s62, 0, 0x1c000
	v_add_u32_e32 v164, s59, v146
	v_add_u32_e32 v180, s62, v146
	ds_read_b128 v[152:155], v164
	ds_read_b128 v[156:159], v164 offset:1024
	ds_read_b128 v[160:163], v164 offset:2048
	ds_read_b128 v[164:167], v164 offset:3072
	ds_read_b128 v[168:171], v180
	ds_read_b128 v[172:175], v180 offset:1024
	ds_read_b128 v[176:179], v180 offset:2048
	ds_read_b128 v[180:183], v180 offset:3072
	s_add_u32 s26, s26, 0x80000
	s_addc_u32 s27, s27, 0
	s_mov_b32 m0, s34
	ds_read_b128 v[184:187], v151 offset:32768
	ds_read_b128 v[188:191], v151 offset:33792
	ds_read_b128 v[192:195], v151 offset:34816
	ds_read_b128 v[196:199], v151 offset:35840
	ds_read_b128 v[200:203], v151 offset:36864
	ds_read_b128 v[204:207], v151 offset:37888
	ds_read_b128 v[208:211], v151 offset:38912
	ds_read_b128 v[212:215], v151 offset:39936
	global_load_lds_dwordx4 v128, s[26:27]
	s_mov_b32 m0, s35
	s_nop 0
	global_load_lds_dwordx4 v132, s[26:27]
	s_waitcnt vmcnt(8)
	s_waitcnt lgkmcnt(0)
	s_barrier
	s_setprio 1
	s_waitcnt lgkmcnt(0)
	v_mfma_f32_16x16x32_bf16 v[124:127], v[152:155], v[184:187], v[124:127]
	v_mfma_f32_16x16x32_bf16 v[120:123], v[160:163], v[184:187], v[120:123]
	v_mfma_f32_16x16x32_bf16 v[116:119], v[152:155], v[192:195], v[116:119]
	v_mfma_f32_16x16x32_bf16 v[108:111], v[160:163], v[192:195], v[108:111]
	v_mfma_f32_16x16x32_bf16 v[100:103], v[152:155], v[200:203], v[100:103]
	v_mfma_f32_16x16x32_bf16 v[92:95], v[160:163], v[200:203], v[92:95]
	v_mfma_f32_16x16x32_bf16 v[84:87], v[152:155], v[208:211], v[84:87]
	v_mfma_f32_16x16x32_bf16 v[76:79], v[160:163], v[208:211], v[76:79]
	v_mfma_f32_16x16x32_bf16 v[124:127], v[156:159], v[188:191], v[124:127]
	v_mfma_f32_16x16x32_bf16 v[120:123], v[164:167], v[188:191], v[120:123]
	v_mfma_f32_16x16x32_bf16 v[116:119], v[156:159], v[196:199], v[116:119]
	v_mfma_f32_16x16x32_bf16 v[108:111], v[164:167], v[196:199], v[108:111]
	v_mfma_f32_16x16x32_bf16 v[100:103], v[156:159], v[204:207], v[100:103]
	v_mfma_f32_16x16x32_bf16 v[92:95], v[164:167], v[204:207], v[92:95]
	v_mfma_f32_16x16x32_bf16 v[84:87], v[156:159], v[212:215], v[84:87]
	v_mfma_f32_16x16x32_bf16 v[76:79], v[164:167], v[212:215], v[76:79]
	s_setprio 0
	s_setprio 1
	v_mfma_f32_16x16x32_bf16 v[112:115], v[168:171], v[184:187], v[112:115]
	v_mfma_f32_16x16x32_bf16 v[104:107], v[176:179], v[184:187], v[104:107]
	v_mfma_f32_16x16x32_bf16 v[96:99], v[168:171], v[192:195], v[96:99]
	v_mfma_f32_16x16x32_bf16 v[88:91], v[176:179], v[192:195], v[88:91]
	v_mfma_f32_16x16x32_bf16 v[80:83], v[168:171], v[200:203], v[80:83]
	v_mfma_f32_16x16x32_bf16 v[72:75], v[176:179], v[200:203], v[72:75]
	v_mfma_f32_16x16x32_bf16 v[68:71], v[168:171], v[208:211], v[68:71]
	v_mfma_f32_16x16x32_bf16 v[64:67], v[176:179], v[208:211], v[64:67]
	v_mfma_f32_16x16x32_bf16 v[112:115], v[172:175], v[188:191], v[112:115]
	v_mfma_f32_16x16x32_bf16 v[104:107], v[180:183], v[188:191], v[104:107]
	v_mfma_f32_16x16x32_bf16 v[96:99], v[172:175], v[196:199], v[96:99]
	v_mfma_f32_16x16x32_bf16 v[88:91], v[180:183], v[196:199], v[88:91]
	v_mfma_f32_16x16x32_bf16 v[80:83], v[172:175], v[204:207], v[80:83]
	v_mfma_f32_16x16x32_bf16 v[72:75], v[180:183], v[204:207], v[72:75]
	v_mfma_f32_16x16x32_bf16 v[68:71], v[172:175], v[212:215], v[68:71]
	v_mfma_f32_16x16x32_bf16 v[64:67], v[180:183], v[212:215], v[64:67]
	s_setprio 0
	s_barrier
	s_add_i32 s26, s59, s28
	s_mov_b32 m0, s26
	ds_read_b128 v[184:187], v151 offset:49152
	ds_read_b128 v[188:191], v151 offset:50176
	ds_read_b128 v[192:195], v151 offset:51200
	ds_read_b128 v[196:199], v151 offset:52224
	ds_read_b128 v[200:203], v151 offset:53248
	ds_read_b128 v[204:207], v151 offset:54272
	ds_read_b128 v[208:211], v151 offset:55296
	ds_read_b128 v[212:215], v151 offset:56320
	global_load_lds_dwordx4 v130, s[98:99]
	s_add_i32 m0, s26, 0x2000
	s_add_u32 s24, s24, 0x200080
	s_addc_u32 s25, s25, 0
	s_add_i32 s26, s62, s28
	global_load_lds_dwordx4 v134, s[98:99]
	s_mov_b32 m0, s26
	s_nop 0
	global_load_lds_dwordx4 v130, s[24:25]
	s_add_i32 m0, s26, 0x2000
	s_nop 0
	global_load_lds_dwordx4 v134, s[24:25]
	s_mov_b32 m0, s37
	s_nop 0
	global_load_lds_dwordx4 v128, s[100:101]
	s_mov_b32 m0, s38
	s_nop 0
	global_load_lds_dwordx4 v132, s[100:101]
	s_waitcnt vmcnt(8)
	s_waitcnt lgkmcnt(0)
	s_barrier
	s_setprio 1
	s_waitcnt lgkmcnt(0)
	v_mfma_f32_16x16x32_bf16 v[60:63], v[152:155], v[184:187], v[60:63]
	v_mfma_f32_16x16x32_bf16 v[56:59], v[160:163], v[184:187], v[56:59]
	v_mfma_f32_16x16x32_bf16 v[52:55], v[152:155], v[192:195], v[52:55]
	v_mfma_f32_16x16x32_bf16 v[44:47], v[160:163], v[192:195], v[44:47]
	v_mfma_f32_16x16x32_bf16 v[36:39], v[152:155], v[200:203], v[36:39]
	v_mfma_f32_16x16x32_bf16 v[28:31], v[160:163], v[200:203], v[28:31]
	v_mfma_f32_16x16x32_bf16 v[20:23], v[152:155], v[208:211], v[20:23]
	v_mfma_f32_16x16x32_bf16 v[12:15], v[160:163], v[208:211], v[12:15]
	v_mfma_f32_16x16x32_bf16 v[60:63], v[156:159], v[188:191], v[60:63]
	v_mfma_f32_16x16x32_bf16 v[56:59], v[164:167], v[188:191], v[56:59]
	v_mfma_f32_16x16x32_bf16 v[52:55], v[156:159], v[196:199], v[52:55]
	v_mfma_f32_16x16x32_bf16 v[44:47], v[164:167], v[196:199], v[44:47]
	v_mfma_f32_16x16x32_bf16 v[36:39], v[156:159], v[204:207], v[36:39]
	v_mfma_f32_16x16x32_bf16 v[28:31], v[164:167], v[204:207], v[28:31]
	v_mfma_f32_16x16x32_bf16 v[20:23], v[156:159], v[212:215], v[20:23]
	v_mfma_f32_16x16x32_bf16 v[12:15], v[164:167], v[212:215], v[12:15]
	s_setprio 0
	s_setprio 1
	v_mfma_f32_16x16x32_bf16 v[48:51], v[168:171], v[184:187], v[48:51]
	v_mfma_f32_16x16x32_bf16 v[40:43], v[176:179], v[184:187], v[40:43]
	v_mfma_f32_16x16x32_bf16 v[32:35], v[168:171], v[192:195], v[32:35]
	v_mfma_f32_16x16x32_bf16 v[24:27], v[176:179], v[192:195], v[24:27]
	v_mfma_f32_16x16x32_bf16 v[16:19], v[168:171], v[200:203], v[16:19]
	v_mfma_f32_16x16x32_bf16 v[8:11], v[176:179], v[200:203], v[8:11]
	v_mfma_f32_16x16x32_bf16 v[4:7], v[168:171], v[208:211], v[4:7]
	v_mfma_f32_16x16x32_bf16 v[0:3], v[176:179], v[208:211], v[0:3]
	v_mfma_f32_16x16x32_bf16 v[48:51], v[172:175], v[188:191], v[48:51]
	v_mfma_f32_16x16x32_bf16 v[40:43], v[180:183], v[188:191], v[40:43]
	v_mfma_f32_16x16x32_bf16 v[32:35], v[172:175], v[196:199], v[32:35]
	v_mfma_f32_16x16x32_bf16 v[24:27], v[180:183], v[196:199], v[24:27]
	v_mfma_f32_16x16x32_bf16 v[16:19], v[172:175], v[204:207], v[16:19]
	v_mfma_f32_16x16x32_bf16 v[8:11], v[180:183], v[204:207], v[8:11]
	v_mfma_f32_16x16x32_bf16 v[4:7], v[172:175], v[212:215], v[4:7]
	v_mfma_f32_16x16x32_bf16 v[0:3], v[180:183], v[212:215], v[0:3]
	s_setprio 0
	s_barrier
	s_add_i32 s58, s58, 2
	s_add_u32 s22, s22, 0x100
	s_addc_u32 s23, s23, 0
	s_add_u32 s56, s56, 0x100
	s_addc_u32 s57, s57, 0
	s_cmp_gt_u32 s58, 29
	s_cbranch_scc0 .LBB0_163
	s_and_b64 vcc, exec, s[10:11]
	s_cbranch_vccz .LBB0_166
	s_barrier

.LBB0_188:
	ds_read_b128 v[154:157], v149
	ds_read_b128 v[158:161], v149 offset:1024
	ds_read_b128 v[162:165], v149 offset:2048
	ds_read_b128 v[166:169], v149 offset:3072
	ds_read_b128 v[170:173], v150
	ds_read_b128 v[174:177], v150 offset:1024
	ds_read_b128 v[178:181], v150 offset:2048
	ds_read_b128 v[182:185], v150 offset:3072
	s_add_u32 s34, s30, 0xfff00080
	s_addc_u32 s35, s31, -1
	s_cmp_eq_u32 s79, 60
	s_cselect_b32 s37, s23, s35
	s_cselect_b32 s36, s73, s34
	s_cselect_b32 s35, s21, s78
	s_cselect_b32 s34, s74, s75
	s_add_u32 s98, s34, s10
	s_addc_u32 s99, s35, s11
	s_add_u32 s100, s36, s10
	s_addc_u32 s101, s37, s11
	s_add_i32 m0, s49, 0xc000
	ds_read_b128 v[186:189], v151
	ds_read_b128 v[190:193], v151 offset:1024
	ds_read_b128 v[194:197], v151 offset:2048
	ds_read_b128 v[198:201], v151 offset:3072
	ds_read_b128 v[202:205], v151 offset:4096
	ds_read_b128 v[206:209], v151 offset:5120
	ds_read_b128 v[210:213], v151 offset:6144
	ds_read_b128 v[214:217], v151 offset:7168
	global_load_lds_dwordx4 v136, s[30:31]
	s_add_i32 m0, s49, 0xe000
	s_nop 0
	global_load_lds_dwordx4 v138, s[30:31]
	s_waitcnt vmcnt(8)
	s_waitcnt lgkmcnt(0)
	s_barrier
	s_setprio 1
	s_waitcnt lgkmcnt(0)
	v_mfma_f32_16x16x32_bf16 v[124:127], v[154:157], v[186:189], v[124:127]
	v_mfma_f32_16x16x32_bf16 v[120:123], v[162:165], v[186:189], v[120:123]
	v_mfma_f32_16x16x32_bf16 v[116:119], v[154:157], v[194:197], v[116:119]
	v_mfma_f32_16x16x32_bf16 v[112:115], v[162:165], v[194:197], v[112:115]
	v_mfma_f32_16x16x32_bf16 v[104:107], v[154:157], v[202:205], v[104:107]
	v_mfma_f32_16x16x32_bf16 v[96:99], v[162:165], v[202:205], v[96:99]
	v_mfma_f32_16x16x32_bf16 v[76:79], v[154:157], v[210:213], v[76:79]
	v_mfma_f32_16x16x32_bf16 v[72:75], v[162:165], v[210:213], v[72:75]
	v_mfma_f32_16x16x32_bf16 v[124:127], v[158:161], v[190:193], v[124:127]
	v_mfma_f32_16x16x32_bf16 v[120:123], v[166:169], v[190:193], v[120:123]
	v_mfma_f32_16x16x32_bf16 v[116:119], v[158:161], v[198:201], v[116:119]
	v_mfma_f32_16x16x32_bf16 v[112:115], v[166:169], v[198:201], v[112:115]
	v_mfma_f32_16x16x32_bf16 v[104:107], v[158:161], v[206:209], v[104:107]
	v_mfma_f32_16x16x32_bf16 v[96:99], v[166:169], v[206:209], v[96:99]
	v_mfma_f32_16x16x32_bf16 v[76:79], v[158:161], v[214:217], v[76:79]
	v_mfma_f32_16x16x32_bf16 v[72:75], v[166:169], v[214:217], v[72:75]
	s_setprio 0
	s_setprio 1
	v_mfma_f32_16x16x32_bf16 v[108:111], v[170:173], v[186:189], v[108:111]
	v_mfma_f32_16x16x32_bf16 v[100:103], v[178:181], v[186:189], v[100:103]
	v_mfma_f32_16x16x32_bf16 v[92:95], v[170:173], v[194:197], v[92:95]
	v_mfma_f32_16x16x32_bf16 v[88:91], v[178:181], v[194:197], v[88:91]
	v_mfma_f32_16x16x32_bf16 v[84:87], v[170:173], v[202:205], v[84:87]
	v_mfma_f32_16x16x32_bf16 v[80:83], v[178:181], v[202:205], v[80:83]
	v_mfma_f32_16x16x32_bf16 v[68:71], v[170:173], v[210:213], v[68:71]
	v_mfma_f32_16x16x32_bf16 v[64:67], v[178:181], v[210:213], v[64:67]
	v_mfma_f32_16x16x32_bf16 v[108:111], v[174:177], v[190:193], v[108:111]
	v_mfma_f32_16x16x32_bf16 v[100:103], v[182:185], v[190:193], v[100:103]
	v_mfma_f32_16x16x32_bf16 v[92:95], v[174:177], v[198:201], v[92:95]
	v_mfma_f32_16x16x32_bf16 v[88:91], v[182:185], v[198:201], v[88:91]
	v_mfma_f32_16x16x32_bf16 v[84:87], v[174:177], v[206:209], v[84:87]
	v_mfma_f32_16x16x32_bf16 v[80:83], v[182:185], v[206:209], v[80:83]
	v_mfma_f32_16x16x32_bf16 v[68:71], v[174:177], v[214:217], v[68:71]
	v_mfma_f32_16x16x32_bf16 v[64:67], v[182:185], v[214:217], v[64:67]
	s_setprio 0
	s_barrier
	s_add_i32 s80, s63, s38
	s_mov_b32 m0, s80
	ds_read_b128 v[186:189], v151 offset:16384
	ds_read_b128 v[190:193], v151 offset:17408
	ds_read_b128 v[194:197], v151 offset:18432
	ds_read_b128 v[198:201], v151 offset:19456
	ds_read_b128 v[202:205], v151 offset:20480
	ds_read_b128 v[206:209], v151 offset:21504
	ds_read_b128 v[210:213], v151 offset:22528
	ds_read_b128 v[214:217], v151 offset:23552
	global_load_lds_dwordx4 v130, s[34:35]
	s_add_i32 m0, s80, 0x2000
	s_add_u32 s80, s34, 0x100000
	s_addc_u32 s81, s35, 0
	s_add_i32 s82, s68, s38
	global_load_lds_dwordx4 v134, s[34:35]
	s_mov_b32 m0, s82
	s_nop 0
	global_load_lds_dwordx4 v130, s[80:81]
	s_add_i32 m0, s82, 0x2000
	s_nop 0
	global_load_lds_dwordx4 v134, s[80:81]
	s_mov_b32 m0, s49
	s_nop 0
	global_load_lds_dwordx4 v128, s[36:37]
	s_mov_b32 m0, s54
	s_nop 0
	global_load_lds_dwordx4 v132, s[36:37]
	s_waitcnt vmcnt(8)
	s_waitcnt lgkmcnt(0)
	s_barrier
	s_setprio 1
	s_waitcnt lgkmcnt(0)
	v_mfma_f32_16x16x32_bf16 v[60:63], v[154:157], v[186:189], v[60:63]
	v_mfma_f32_16x16x32_bf16 v[56:59], v[162:165], v[186:189], v[56:59]
	v_mfma_f32_16x16x32_bf16 v[44:47], v[154:157], v[194:197], v[44:47]
	v_mfma_f32_16x16x32_bf16 v[40:43], v[162:165], v[194:197], v[40:43]
	v_mfma_f32_16x16x32_bf16 v[28:31], v[154:157], v[202:205], v[28:31]
	v_mfma_f32_16x16x32_bf16 v[24:27], v[162:165], v[202:205], v[24:27]
	v_mfma_f32_16x16x32_bf16 v[12:15], v[154:157], v[210:213], v[12:15]
	v_mfma_f32_16x16x32_bf16 v[8:11], v[162:165], v[210:213], v[8:11]
	v_mfma_f32_16x16x32_bf16 v[60:63], v[158:161], v[190:193], v[60:63]
	v_mfma_f32_16x16x32_bf16 v[56:59], v[166:169], v[190:193], v[56:59]
	v_mfma_f32_16x16x32_bf16 v[44:47], v[158:161], v[198:201], v[44:47]
	v_mfma_f32_16x16x32_bf16 v[40:43], v[166:169], v[198:201], v[40:43]
	v_mfma_f32_16x16x32_bf16 v[28:31], v[158:161], v[206:209], v[28:31]
	v_mfma_f32_16x16x32_bf16 v[24:27], v[166:169], v[206:209], v[24:27]
	v_mfma_f32_16x16x32_bf16 v[12:15], v[158:161], v[214:217], v[12:15]
	v_mfma_f32_16x16x32_bf16 v[8:11], v[166:169], v[214:217], v[8:11]
	s_setprio 0
	s_setprio 1
	v_mfma_f32_16x16x32_bf16 v[52:55], v[170:173], v[186:189], v[52:55]
	v_mfma_f32_16x16x32_bf16 v[48:51], v[178:181], v[186:189], v[48:51]
	v_mfma_f32_16x16x32_bf16 v[36:39], v[170:173], v[194:197], v[36:39]
	v_mfma_f32_16x16x32_bf16 v[32:35], v[178:181], v[194:197], v[32:35]
	v_mfma_f32_16x16x32_bf16 v[20:23], v[170:173], v[202:205], v[20:23]
	v_mfma_f32_16x16x32_bf16 v[16:19], v[178:181], v[202:205], v[16:19]
	v_mfma_f32_16x16x32_bf16 v[4:7], v[170:173], v[210:213], v[4:7]
	v_mfma_f32_16x16x32_bf16 v[0:3], v[178:181], v[210:213], v[0:3]
	v_mfma_f32_16x16x32_bf16 v[52:55], v[174:177], v[190:193], v[52:55]
	v_mfma_f32_16x16x32_bf16 v[48:51], v[182:185], v[190:193], v[48:51]
	v_mfma_f32_16x16x32_bf16 v[36:39], v[174:177], v[198:201], v[36:39]
	v_mfma_f32_16x16x32_bf16 v[32:35], v[182:185], v[198:201], v[32:35]
	v_mfma_f32_16x16x32_bf16 v[20:23], v[174:177], v[206:209], v[20:23]
	v_mfma_f32_16x16x32_bf16 v[16:19], v[182:185], v[206:209], v[16:19]
	v_mfma_f32_16x16x32_bf16 v[4:7], v[174:177], v[214:217], v[4:7]
	v_mfma_f32_16x16x32_bf16 v[0:3], v[182:185], v[214:217], v[0:3]
	s_setprio 0
	s_barrier
	s_add_i32 s80, 0, 0x18000
	s_add_i32 s81, 0, 0x1c000
	v_add_u32_e32 v166, s80, v147
	v_add_u32_e32 v182, s81, v147
	ds_read_b128 v[154:157], v166
	ds_read_b128 v[158:161], v166 offset:1024
	ds_read_b128 v[162:165], v166 offset:2048
	ds_read_b128 v[166:169], v166 offset:3072
	ds_read_b128 v[170:173], v182
	ds_read_b128 v[174:177], v182 offset:1024
	ds_read_b128 v[178:181], v182 offset:2048
	ds_read_b128 v[182:185], v182 offset:3072
	s_add_u32 s36, s36, 0x100000
	s_addc_u32 s37, s37, 0
	s_mov_b32 m0, s55
	ds_read_b128 v[186:189], v151 offset:32768
	ds_read_b128 v[190:193], v151 offset:33792
	ds_read_b128 v[194:197], v151 offset:34816
	ds_read_b128 v[198:201], v151 offset:35840
	ds_read_b128 v[202:205], v151 offset:36864
	ds_read_b128 v[206:209], v151 offset:37888
	ds_read_b128 v[210:213], v151 offset:38912
	ds_read_b128 v[214:217], v151 offset:39936
	global_load_lds_dwordx4 v128, s[36:37]
	s_mov_b32 m0, s56
	s_nop 0
	global_load_lds_dwordx4 v132, s[36:37]
	s_waitcnt vmcnt(8)
	s_waitcnt lgkmcnt(0)
	s_barrier
	s_setprio 1
	s_waitcnt lgkmcnt(0)
	v_mfma_f32_16x16x32_bf16 v[124:127], v[154:157], v[186:189], v[124:127]
	v_mfma_f32_16x16x32_bf16 v[120:123], v[162:165], v[186:189], v[120:123]
	v_mfma_f32_16x16x32_bf16 v[116:119], v[154:157], v[194:197], v[116:119]
	v_mfma_f32_16x16x32_bf16 v[112:115], v[162:165], v[194:197], v[112:115]
	v_mfma_f32_16x16x32_bf16 v[104:107], v[154:157], v[202:205], v[104:107]
	v_mfma_f32_16x16x32_bf16 v[96:99], v[162:165], v[202:205], v[96:99]
	v_mfma_f32_16x16x32_bf16 v[76:79], v[154:157], v[210:213], v[76:79]
	v_mfma_f32_16x16x32_bf16 v[72:75], v[162:165], v[210:213], v[72:75]
	v_mfma_f32_16x16x32_bf16 v[124:127], v[158:161], v[190:193], v[124:127]
	v_mfma_f32_16x16x32_bf16 v[120:123], v[166:169], v[190:193], v[120:123]
	v_mfma_f32_16x16x32_bf16 v[116:119], v[158:161], v[198:201], v[116:119]
	v_mfma_f32_16x16x32_bf16 v[112:115], v[166:169], v[198:201], v[112:115]
	v_mfma_f32_16x16x32_bf16 v[104:107], v[158:161], v[206:209], v[104:107]
	v_mfma_f32_16x16x32_bf16 v[96:99], v[166:169], v[206:209], v[96:99]
	v_mfma_f32_16x16x32_bf16 v[76:79], v[158:161], v[214:217], v[76:79]
	v_mfma_f32_16x16x32_bf16 v[72:75], v[166:169], v[214:217], v[72:75]
	s_setprio 0
	s_setprio 1
	v_mfma_f32_16x16x32_bf16 v[108:111], v[170:173], v[186:189], v[108:111]
	v_mfma_f32_16x16x32_bf16 v[100:103], v[178:181], v[186:189], v[100:103]
	v_mfma_f32_16x16x32_bf16 v[92:95], v[170:173], v[194:197], v[92:95]
	v_mfma_f32_16x16x32_bf16 v[88:91], v[178:181], v[194:197], v[88:91]
	v_mfma_f32_16x16x32_bf16 v[84:87], v[170:173], v[202:205], v[84:87]
	v_mfma_f32_16x16x32_bf16 v[80:83], v[178:181], v[202:205], v[80:83]
	v_mfma_f32_16x16x32_bf16 v[68:71], v[170:173], v[210:213], v[68:71]
	v_mfma_f32_16x16x32_bf16 v[64:67], v[178:181], v[210:213], v[64:67]
	v_mfma_f32_16x16x32_bf16 v[108:111], v[174:177], v[190:193], v[108:111]
	v_mfma_f32_16x16x32_bf16 v[100:103], v[182:185], v[190:193], v[100:103]
	v_mfma_f32_16x16x32_bf16 v[92:95], v[174:177], v[198:201], v[92:95]
	v_mfma_f32_16x16x32_bf16 v[88:91], v[182:185], v[198:201], v[88:91]
	v_mfma_f32_16x16x32_bf16 v[84:87], v[174:177], v[206:209], v[84:87]
	v_mfma_f32_16x16x32_bf16 v[80:83], v[182:185], v[206:209], v[80:83]
	v_mfma_f32_16x16x32_bf16 v[68:71], v[174:177], v[214:217], v[68:71]
	v_mfma_f32_16x16x32_bf16 v[64:67], v[182:185], v[214:217], v[64:67]
	s_setprio 0
	s_barrier
	s_add_i32 s36, s80, s38
	s_mov_b32 m0, s36
	ds_read_b128 v[186:189], v151 offset:49152
	ds_read_b128 v[190:193], v151 offset:50176
	ds_read_b128 v[194:197], v151 offset:51200
	ds_read_b128 v[198:201], v151 offset:52224
	ds_read_b128 v[202:205], v151 offset:53248
	ds_read_b128 v[206:209], v151 offset:54272
	ds_read_b128 v[210:213], v151 offset:55296
	ds_read_b128 v[214:217], v151 offset:56320
	global_load_lds_dwordx4 v130, s[98:99]
	s_add_i32 m0, s36, 0x2000
	s_add_u32 s34, s34, 0x100080
	s_addc_u32 s35, s35, 0
	s_add_i32 s36, s81, s38
	global_load_lds_dwordx4 v134, s[98:99]
	s_mov_b32 m0, s36
	s_nop 0
	global_load_lds_dwordx4 v130, s[34:35]
	s_add_i32 m0, s36, 0x2000
	s_nop 0
	global_load_lds_dwordx4 v134, s[34:35]
	s_mov_b32 m0, s58
	s_nop 0
	global_load_lds_dwordx4 v128, s[100:101]
	s_mov_b32 m0, s59
	s_nop 0
	global_load_lds_dwordx4 v132, s[100:101]
	s_waitcnt vmcnt(8)
	s_waitcnt lgkmcnt(0)
	s_barrier
	s_setprio 1
	s_waitcnt lgkmcnt(0)
	v_mfma_f32_16x16x32_bf16 v[60:63], v[154:157], v[186:189], v[60:63]
	v_mfma_f32_16x16x32_bf16 v[56:59], v[162:165], v[186:189], v[56:59]
	v_mfma_f32_16x16x32_bf16 v[44:47], v[154:157], v[194:197], v[44:47]
	v_mfma_f32_16x16x32_bf16 v[40:43], v[162:165], v[194:197], v[40:43]
	v_mfma_f32_16x16x32_bf16 v[28:31], v[154:157], v[202:205], v[28:31]
	v_mfma_f32_16x16x32_bf16 v[24:27], v[162:165], v[202:205], v[24:27]
	v_mfma_f32_16x16x32_bf16 v[12:15], v[154:157], v[210:213], v[12:15]
	v_mfma_f32_16x16x32_bf16 v[8:11], v[162:165], v[210:213], v[8:11]
	v_mfma_f32_16x16x32_bf16 v[60:63], v[158:161], v[190:193], v[60:63]
	v_mfma_f32_16x16x32_bf16 v[56:59], v[166:169], v[190:193], v[56:59]
	v_mfma_f32_16x16x32_bf16 v[44:47], v[158:161], v[198:201], v[44:47]
	v_mfma_f32_16x16x32_bf16 v[40:43], v[166:169], v[198:201], v[40:43]
	v_mfma_f32_16x16x32_bf16 v[28:31], v[158:161], v[206:209], v[28:31]
	v_mfma_f32_16x16x32_bf16 v[24:27], v[166:169], v[206:209], v[24:27]
	v_mfma_f32_16x16x32_bf16 v[12:15], v[158:161], v[214:217], v[12:15]
	v_mfma_f32_16x16x32_bf16 v[8:11], v[166:169], v[214:217], v[8:11]
	s_setprio 0
	s_setprio 1
	v_mfma_f32_16x16x32_bf16 v[52:55], v[170:173], v[186:189], v[52:55]
	v_mfma_f32_16x16x32_bf16 v[48:51], v[178:181], v[186:189], v[48:51]
	v_mfma_f32_16x16x32_bf16 v[36:39], v[170:173], v[194:197], v[36:39]
	v_mfma_f32_16x16x32_bf16 v[32:35], v[178:181], v[194:197], v[32:35]
	v_mfma_f32_16x16x32_bf16 v[20:23], v[170:173], v[202:205], v[20:23]
	v_mfma_f32_16x16x32_bf16 v[16:19], v[178:181], v[202:205], v[16:19]
	v_mfma_f32_16x16x32_bf16 v[4:7], v[170:173], v[210:213], v[4:7]
	v_mfma_f32_16x16x32_bf16 v[0:3], v[178:181], v[210:213], v[0:3]
	v_mfma_f32_16x16x32_bf16 v[52:55], v[174:177], v[190:193], v[52:55]
	v_mfma_f32_16x16x32_bf16 v[48:51], v[182:185], v[190:193], v[48:51]
	v_mfma_f32_16x16x32_bf16 v[36:39], v[174:177], v[198:201], v[36:39]
	v_mfma_f32_16x16x32_bf16 v[32:35], v[182:185], v[198:201], v[32:35]
	v_mfma_f32_16x16x32_bf16 v[20:23], v[174:177], v[206:209], v[20:23]
	v_mfma_f32_16x16x32_bf16 v[16:19], v[182:185], v[206:209], v[16:19]
	v_mfma_f32_16x16x32_bf16 v[4:7], v[174:177], v[214:217], v[4:7]
	v_mfma_f32_16x16x32_bf16 v[0:3], v[182:185], v[214:217], v[0:3]
	s_setprio 0
	s_barrier
	s_add_i32 s79, s79, 2
	s_add_u32 s30, s30, 0x100
	s_addc_u32 s31, s31, 0
	s_add_u32 s75, s75, 0x100
	s_addc_u32 s78, s78, 0
	s_cmp_gt_u32 s79, 61
	s_cbranch_scc0 .LBB0_188
	s_and_b64 vcc, exec, s[12:13]
	s_cbranch_vccz .LBB0_191
	s_barrier

.LBB0_431:
	ds_read_b128 v[128:131], v207
	ds_read_b128 v[132:135], v207 offset:1024
	ds_read_b128 v[136:139], v207 offset:2048
	ds_read_b128 v[140:143], v207 offset:3072
	ds_read_b128 v[144:147], v208
	ds_read_b128 v[148:151], v208 offset:1024
	ds_read_b128 v[152:155], v208 offset:2048
	ds_read_b128 v[156:159], v208 offset:3072
	s_add_u32 s28, s26, 0xfff00080
	s_addc_u32 s29, s27, -1
	s_cmp_eq_u32 s55, 60
	s_cselect_b32 s31, s15, s29
	s_cselect_b32 s30, s21, s28
	s_cselect_b32 s29, s13, s54
	s_cselect_b32 s28, s52, s53
	s_add_u32 s98, s28, s8
	s_addc_u32 s99, s29, s9
	s_add_u32 s100, s30, s8
	s_addc_u32 s101, s31, s9
	s_add_i32 m0, s23, 0xc000
	ds_read_b128 v[160:163], v209
	ds_read_b128 v[164:167], v209 offset:1024
	ds_read_b128 v[168:171], v209 offset:2048
	ds_read_b128 v[172:175], v209 offset:3072
	ds_read_b128 v[192:195], v209 offset:4096
	ds_read_b128 v[196:199], v209 offset:5120
	ds_read_b128 v[200:203], v209 offset:6144
	ds_read_b128 v[212:215], v209 offset:7168
	global_load_lds_dwordx4 v184, s[26:27]
	s_add_i32 m0, s23, 0xe000
	s_nop 0
	global_load_lds_dwordx4 v186, s[26:27]
	s_waitcnt vmcnt(8)
	s_waitcnt lgkmcnt(0)
	s_barrier
	s_setprio 1
	s_waitcnt lgkmcnt(0)
	v_mfma_f32_16x16x32_bf16 v[124:127], v[128:131], v[160:163], v[124:127]
	v_mfma_f32_16x16x32_bf16 v[120:123], v[136:139], v[160:163], v[120:123]
	v_mfma_f32_16x16x32_bf16 v[108:111], v[128:131], v[168:171], v[108:111]
	v_mfma_f32_16x16x32_bf16 v[104:107], v[136:139], v[168:171], v[104:107]
	v_mfma_f32_16x16x32_bf16 v[92:95], v[128:131], v[192:195], v[92:95]
	v_mfma_f32_16x16x32_bf16 v[88:91], v[136:139], v[192:195], v[88:91]
	v_mfma_f32_16x16x32_bf16 v[76:79], v[128:131], v[200:203], v[76:79]
	v_mfma_f32_16x16x32_bf16 v[72:75], v[136:139], v[200:203], v[72:75]
	v_mfma_f32_16x16x32_bf16 v[124:127], v[132:135], v[164:167], v[124:127]
	v_mfma_f32_16x16x32_bf16 v[120:123], v[140:143], v[164:167], v[120:123]
	v_mfma_f32_16x16x32_bf16 v[108:111], v[132:135], v[172:175], v[108:111]
	v_mfma_f32_16x16x32_bf16 v[104:107], v[140:143], v[172:175], v[104:107]
	v_mfma_f32_16x16x32_bf16 v[92:95], v[132:135], v[196:199], v[92:95]
	v_mfma_f32_16x16x32_bf16 v[88:91], v[140:143], v[196:199], v[88:91]
	v_mfma_f32_16x16x32_bf16 v[76:79], v[132:135], v[212:215], v[76:79]
	v_mfma_f32_16x16x32_bf16 v[72:75], v[140:143], v[212:215], v[72:75]
	s_setprio 0
	s_setprio 1
	v_mfma_f32_16x16x32_bf16 v[116:119], v[144:147], v[160:163], v[116:119]
	v_mfma_f32_16x16x32_bf16 v[112:115], v[152:155], v[160:163], v[112:115]
	v_mfma_f32_16x16x32_bf16 v[100:103], v[144:147], v[168:171], v[100:103]
	v_mfma_f32_16x16x32_bf16 v[96:99], v[152:155], v[168:171], v[96:99]
	v_mfma_f32_16x16x32_bf16 v[84:87], v[144:147], v[192:195], v[84:87]
	v_mfma_f32_16x16x32_bf16 v[80:83], v[152:155], v[192:195], v[80:83]
	v_mfma_f32_16x16x32_bf16 v[68:71], v[144:147], v[200:203], v[68:71]
	v_mfma_f32_16x16x32_bf16 v[64:67], v[152:155], v[200:203], v[64:67]
	v_mfma_f32_16x16x32_bf16 v[116:119], v[148:151], v[164:167], v[116:119]
	v_mfma_f32_16x16x32_bf16 v[112:115], v[156:159], v[164:167], v[112:115]
	v_mfma_f32_16x16x32_bf16 v[100:103], v[148:151], v[172:175], v[100:103]
	v_mfma_f32_16x16x32_bf16 v[96:99], v[156:159], v[172:175], v[96:99]
	v_mfma_f32_16x16x32_bf16 v[84:87], v[148:151], v[196:199], v[84:87]
	v_mfma_f32_16x16x32_bf16 v[80:83], v[156:159], v[196:199], v[80:83]
	v_mfma_f32_16x16x32_bf16 v[68:71], v[148:151], v[212:215], v[68:71]
	v_mfma_f32_16x16x32_bf16 v[64:67], v[156:159], v[212:215], v[64:67]
	s_setprio 0
	s_barrier
	s_add_i32 s58, s50, s3
	s_mov_b32 m0, s58
	ds_read_b128 v[160:163], v209 offset:16384
	ds_read_b128 v[164:167], v209 offset:17408
	ds_read_b128 v[168:171], v209 offset:18432
	ds_read_b128 v[172:175], v209 offset:19456
	ds_read_b128 v[192:195], v209 offset:20480
	ds_read_b128 v[196:199], v209 offset:21504
	ds_read_b128 v[200:203], v209 offset:22528
	ds_read_b128 v[212:215], v209 offset:23552
	global_load_lds_dwordx4 v178, s[28:29]
	s_add_i32 m0, s58, 0x2000
	s_add_u32 s58, s28, 0x100000
	s_addc_u32 s59, s29, 0
	s_add_i32 s62, s51, s3
	global_load_lds_dwordx4 v182, s[28:29]
	s_mov_b32 m0, s62
	s_nop 0
	global_load_lds_dwordx4 v178, s[58:59]
	s_add_i32 m0, s62, 0x2000
	s_nop 0
	global_load_lds_dwordx4 v182, s[58:59]
	s_mov_b32 m0, s23
	s_nop 0
	global_load_lds_dwordx4 v176, s[30:31]
	s_mov_b32 m0, s34
	s_nop 0
	global_load_lds_dwordx4 v180, s[30:31]
	s_waitcnt vmcnt(8)
	s_waitcnt lgkmcnt(0)
	s_barrier
	s_setprio 1
	s_waitcnt lgkmcnt(0)
	v_mfma_f32_16x16x32_bf16 v[60:63], v[128:131], v[160:163], v[60:63]
	v_mfma_f32_16x16x32_bf16 v[56:59], v[136:139], v[160:163], v[56:59]
	v_mfma_f32_16x16x32_bf16 v[44:47], v[128:131], v[168:171], v[44:47]
	v_mfma_f32_16x16x32_bf16 v[40:43], v[136:139], v[168:171], v[40:43]
	v_mfma_f32_16x16x32_bf16 v[28:31], v[128:131], v[192:195], v[28:31]
	v_mfma_f32_16x16x32_bf16 v[24:27], v[136:139], v[192:195], v[24:27]
	v_mfma_f32_16x16x32_bf16 v[12:15], v[128:131], v[200:203], v[12:15]
	v_mfma_f32_16x16x32_bf16 v[8:11], v[136:139], v[200:203], v[8:11]
	v_mfma_f32_16x16x32_bf16 v[60:63], v[132:135], v[164:167], v[60:63]
	v_mfma_f32_16x16x32_bf16 v[56:59], v[140:143], v[164:167], v[56:59]
	v_mfma_f32_16x16x32_bf16 v[44:47], v[132:135], v[172:175], v[44:47]
	v_mfma_f32_16x16x32_bf16 v[40:43], v[140:143], v[172:175], v[40:43]
	v_mfma_f32_16x16x32_bf16 v[28:31], v[132:135], v[196:199], v[28:31]
	v_mfma_f32_16x16x32_bf16 v[24:27], v[140:143], v[196:199], v[24:27]
	v_mfma_f32_16x16x32_bf16 v[12:15], v[132:135], v[212:215], v[12:15]
	v_mfma_f32_16x16x32_bf16 v[8:11], v[140:143], v[212:215], v[8:11]
	s_setprio 0
	s_setprio 1
	v_mfma_f32_16x16x32_bf16 v[52:55], v[144:147], v[160:163], v[52:55]
	v_mfma_f32_16x16x32_bf16 v[48:51], v[152:155], v[160:163], v[48:51]
	v_mfma_f32_16x16x32_bf16 v[36:39], v[144:147], v[168:171], v[36:39]
	v_mfma_f32_16x16x32_bf16 v[32:35], v[152:155], v[168:171], v[32:35]
	v_mfma_f32_16x16x32_bf16 v[20:23], v[144:147], v[192:195], v[20:23]
	v_mfma_f32_16x16x32_bf16 v[16:19], v[152:155], v[192:195], v[16:19]
	v_mfma_f32_16x16x32_bf16 v[4:7], v[144:147], v[200:203], v[4:7]
	v_mfma_f32_16x16x32_bf16 v[0:3], v[152:155], v[200:203], v[0:3]
	v_mfma_f32_16x16x32_bf16 v[52:55], v[148:151], v[164:167], v[52:55]
	v_mfma_f32_16x16x32_bf16 v[48:51], v[156:159], v[164:167], v[48:51]
	v_mfma_f32_16x16x32_bf16 v[36:39], v[148:151], v[172:175], v[36:39]
	v_mfma_f32_16x16x32_bf16 v[32:35], v[156:159], v[172:175], v[32:35]
	v_mfma_f32_16x16x32_bf16 v[20:23], v[148:151], v[196:199], v[20:23]
	v_mfma_f32_16x16x32_bf16 v[16:19], v[156:159], v[196:199], v[16:19]
	v_mfma_f32_16x16x32_bf16 v[4:7], v[148:151], v[212:215], v[4:7]
	v_mfma_f32_16x16x32_bf16 v[0:3], v[156:159], v[212:215], v[0:3]
	s_setprio 0
	s_barrier
	s_add_i32 s58, 0, 0x18000
	s_add_i32 s59, 0, 0x1c000
	v_add_u32_e32 v140, s58, v205
	v_add_u32_e32 v156, s59, v205
	ds_read_b128 v[128:131], v140
	ds_read_b128 v[132:135], v140 offset:1024
	ds_read_b128 v[136:139], v140 offset:2048
	ds_read_b128 v[140:143], v140 offset:3072
	ds_read_b128 v[144:147], v156
	ds_read_b128 v[148:151], v156 offset:1024
	ds_read_b128 v[152:155], v156 offset:2048
	ds_read_b128 v[156:159], v156 offset:3072
	s_add_u32 s30, s30, 0x100000
	s_addc_u32 s31, s31, 0
	s_mov_b32 m0, s35
	ds_read_b128 v[160:163], v209 offset:32768
	ds_read_b128 v[164:167], v209 offset:33792
	ds_read_b128 v[168:171], v209 offset:34816
	ds_read_b128 v[172:175], v209 offset:35840
	ds_read_b128 v[192:195], v209 offset:36864
	ds_read_b128 v[196:199], v209 offset:37888
	ds_read_b128 v[200:203], v209 offset:38912
	ds_read_b128 v[212:215], v209 offset:39936
	global_load_lds_dwordx4 v176, s[30:31]
	s_mov_b32 m0, s36
	s_nop 0
	global_load_lds_dwordx4 v180, s[30:31]
	s_waitcnt vmcnt(8)
	s_waitcnt lgkmcnt(0)
	s_barrier
	s_setprio 1
	s_waitcnt lgkmcnt(0)
	v_mfma_f32_16x16x32_bf16 v[124:127], v[128:131], v[160:163], v[124:127]
	v_mfma_f32_16x16x32_bf16 v[120:123], v[136:139], v[160:163], v[120:123]
	v_mfma_f32_16x16x32_bf16 v[108:111], v[128:131], v[168:171], v[108:111]
	v_mfma_f32_16x16x32_bf16 v[104:107], v[136:139], v[168:171], v[104:107]
	v_mfma_f32_16x16x32_bf16 v[92:95], v[128:131], v[192:195], v[92:95]
	v_mfma_f32_16x16x32_bf16 v[88:91], v[136:139], v[192:195], v[88:91]
	v_mfma_f32_16x16x32_bf16 v[76:79], v[128:131], v[200:203], v[76:79]
	v_mfma_f32_16x16x32_bf16 v[72:75], v[136:139], v[200:203], v[72:75]
	v_mfma_f32_16x16x32_bf16 v[124:127], v[132:135], v[164:167], v[124:127]
	v_mfma_f32_16x16x32_bf16 v[120:123], v[140:143], v[164:167], v[120:123]
	v_mfma_f32_16x16x32_bf16 v[108:111], v[132:135], v[172:175], v[108:111]
	v_mfma_f32_16x16x32_bf16 v[104:107], v[140:143], v[172:175], v[104:107]
	v_mfma_f32_16x16x32_bf16 v[92:95], v[132:135], v[196:199], v[92:95]
	v_mfma_f32_16x16x32_bf16 v[88:91], v[140:143], v[196:199], v[88:91]
	v_mfma_f32_16x16x32_bf16 v[76:79], v[132:135], v[212:215], v[76:79]
	v_mfma_f32_16x16x32_bf16 v[72:75], v[140:143], v[212:215], v[72:75]
	s_setprio 0
	s_setprio 1
	v_mfma_f32_16x16x32_bf16 v[116:119], v[144:147], v[160:163], v[116:119]
	v_mfma_f32_16x16x32_bf16 v[112:115], v[152:155], v[160:163], v[112:115]
	v_mfma_f32_16x16x32_bf16 v[100:103], v[144:147], v[168:171], v[100:103]
	v_mfma_f32_16x16x32_bf16 v[96:99], v[152:155], v[168:171], v[96:99]
	v_mfma_f32_16x16x32_bf16 v[84:87], v[144:147], v[192:195], v[84:87]
	v_mfma_f32_16x16x32_bf16 v[80:83], v[152:155], v[192:195], v[80:83]
	v_mfma_f32_16x16x32_bf16 v[68:71], v[144:147], v[200:203], v[68:71]
	v_mfma_f32_16x16x32_bf16 v[64:67], v[152:155], v[200:203], v[64:67]
	v_mfma_f32_16x16x32_bf16 v[116:119], v[148:151], v[164:167], v[116:119]
	v_mfma_f32_16x16x32_bf16 v[112:115], v[156:159], v[164:167], v[112:115]
	v_mfma_f32_16x16x32_bf16 v[100:103], v[148:151], v[172:175], v[100:103]
	v_mfma_f32_16x16x32_bf16 v[96:99], v[156:159], v[172:175], v[96:99]
	v_mfma_f32_16x16x32_bf16 v[84:87], v[148:151], v[196:199], v[84:87]
	v_mfma_f32_16x16x32_bf16 v[80:83], v[156:159], v[196:199], v[80:83]
	v_mfma_f32_16x16x32_bf16 v[68:71], v[148:151], v[212:215], v[68:71]
	v_mfma_f32_16x16x32_bf16 v[64:67], v[156:159], v[212:215], v[64:67]
	s_setprio 0
	s_barrier
	s_add_i32 s30, s58, s3
	s_mov_b32 m0, s30
	ds_read_b128 v[160:163], v209 offset:49152
	ds_read_b128 v[164:167], v209 offset:50176
	ds_read_b128 v[168:171], v209 offset:51200
	ds_read_b128 v[172:175], v209 offset:52224
	ds_read_b128 v[192:195], v209 offset:53248
	ds_read_b128 v[196:199], v209 offset:54272
	ds_read_b128 v[200:203], v209 offset:55296
	ds_read_b128 v[212:215], v209 offset:56320
	global_load_lds_dwordx4 v178, s[98:99]
	s_add_i32 m0, s30, 0x2000
	s_add_u32 s28, s28, 0x100080
	s_addc_u32 s29, s29, 0
	s_add_i32 s30, s59, s3
	global_load_lds_dwordx4 v182, s[98:99]
	s_mov_b32 m0, s30
	s_nop 0
	global_load_lds_dwordx4 v178, s[28:29]
	s_add_i32 m0, s30, 0x2000
	s_nop 0
	global_load_lds_dwordx4 v182, s[28:29]
	s_mov_b32 m0, s38
	s_nop 0
	global_load_lds_dwordx4 v176, s[100:101]
	s_mov_b32 m0, s39
	s_nop 0
	global_load_lds_dwordx4 v180, s[100:101]
	s_waitcnt vmcnt(8)
	s_waitcnt lgkmcnt(0)
	s_barrier
	s_setprio 1
	s_waitcnt lgkmcnt(0)
	v_mfma_f32_16x16x32_bf16 v[60:63], v[128:131], v[160:163], v[60:63]
	v_mfma_f32_16x16x32_bf16 v[56:59], v[136:139], v[160:163], v[56:59]
	v_mfma_f32_16x16x32_bf16 v[44:47], v[128:131], v[168:171], v[44:47]
	v_mfma_f32_16x16x32_bf16 v[40:43], v[136:139], v[168:171], v[40:43]
	v_mfma_f32_16x16x32_bf16 v[28:31], v[128:131], v[192:195], v[28:31]
	v_mfma_f32_16x16x32_bf16 v[24:27], v[136:139], v[192:195], v[24:27]
	v_mfma_f32_16x16x32_bf16 v[12:15], v[128:131], v[200:203], v[12:15]
	v_mfma_f32_16x16x32_bf16 v[8:11], v[136:139], v[200:203], v[8:11]
	v_mfma_f32_16x16x32_bf16 v[60:63], v[132:135], v[164:167], v[60:63]
	v_mfma_f32_16x16x32_bf16 v[56:59], v[140:143], v[164:167], v[56:59]
	v_mfma_f32_16x16x32_bf16 v[44:47], v[132:135], v[172:175], v[44:47]
	v_mfma_f32_16x16x32_bf16 v[40:43], v[140:143], v[172:175], v[40:43]
	v_mfma_f32_16x16x32_bf16 v[28:31], v[132:135], v[196:199], v[28:31]
	v_mfma_f32_16x16x32_bf16 v[24:27], v[140:143], v[196:199], v[24:27]
	v_mfma_f32_16x16x32_bf16 v[12:15], v[132:135], v[212:215], v[12:15]
	v_mfma_f32_16x16x32_bf16 v[8:11], v[140:143], v[212:215], v[8:11]
	s_setprio 0
	s_setprio 1
	v_mfma_f32_16x16x32_bf16 v[52:55], v[144:147], v[160:163], v[52:55]
	v_mfma_f32_16x16x32_bf16 v[48:51], v[152:155], v[160:163], v[48:51]
	v_mfma_f32_16x16x32_bf16 v[36:39], v[144:147], v[168:171], v[36:39]
	v_mfma_f32_16x16x32_bf16 v[32:35], v[152:155], v[168:171], v[32:35]
	v_mfma_f32_16x16x32_bf16 v[20:23], v[144:147], v[192:195], v[20:23]
	v_mfma_f32_16x16x32_bf16 v[16:19], v[152:155], v[192:195], v[16:19]
	v_mfma_f32_16x16x32_bf16 v[4:7], v[144:147], v[200:203], v[4:7]
	v_mfma_f32_16x16x32_bf16 v[0:3], v[152:155], v[200:203], v[0:3]
	v_mfma_f32_16x16x32_bf16 v[52:55], v[148:151], v[164:167], v[52:55]
	v_mfma_f32_16x16x32_bf16 v[48:51], v[156:159], v[164:167], v[48:51]
	v_mfma_f32_16x16x32_bf16 v[36:39], v[148:151], v[172:175], v[36:39]
	v_mfma_f32_16x16x32_bf16 v[32:35], v[156:159], v[172:175], v[32:35]
	v_mfma_f32_16x16x32_bf16 v[20:23], v[148:151], v[196:199], v[20:23]
	v_mfma_f32_16x16x32_bf16 v[16:19], v[156:159], v[196:199], v[16:19]
	v_mfma_f32_16x16x32_bf16 v[4:7], v[148:151], v[212:215], v[4:7]
	v_mfma_f32_16x16x32_bf16 v[0:3], v[156:159], v[212:215], v[0:3]
	s_setprio 0
	s_barrier
	s_add_i32 s55, s55, 2
	s_add_u32 s26, s26, 0x100
	s_addc_u32 s27, s27, 0
	s_add_u32 s53, s53, 0x100
	s_addc_u32 s54, s54, 0
	s_cmp_gt_u32 s55, 61
	s_cbranch_scc0 .LBB0_431
	s_and_b64 vcc, exec, s[10:11]
	s_cbranch_vccz .LBB0_434
	s_barrier

.LBB0_528:
	ds_read_b128 v[134:137], v200
	ds_read_b128 v[138:141], v200 offset:1024
	ds_read_b128 v[162:165], v200 offset:2048
	ds_read_b128 v[166:169], v200 offset:3072
	ds_read_b128 v[170:173], v201
	ds_read_b128 v[174:177], v201 offset:1024
	ds_read_b128 v[178:181], v201 offset:2048
	ds_read_b128 v[206:209], v201 offset:3072
	s_add_u32 s62, s20, 0xfff00080
	s_addc_u32 s63, s21, -1
	s_cmp_eq_u32 s83, 60
	s_cselect_b32 s79, s47, s63
	s_cselect_b32 s78, s57, s62
	s_cselect_b32 s63, s41, s82
	s_cselect_b32 s62, s59, s81
	s_add_u32 s98, s62, s30
	s_addc_u32 s99, s63, s31
	s_add_u32 s100, s78, s30
	s_addc_u32 s101, s79, s31
	s_add_i32 m0, s39, 0xc000
	ds_read_b128 v[210:213], v202
	ds_read_b128 v[214:217], v202 offset:1024
	ds_read_b128 v[218:221], v202 offset:2048
	ds_read_b128 v[222:225], v202 offset:3072
	ds_read_b128 v[226:229], v202 offset:4096
	ds_read_b128 v[230:233], v202 offset:5120
	ds_read_b128 v[234:237], v202 offset:6144
	ds_read_b128 v[238:241], v202 offset:7168
	global_load_lds_dwordx4 v154, s[20:21]
	s_add_i32 m0, s39, 0xe000
	s_nop 0
	global_load_lds_dwordx4 v156, s[20:21]
	s_waitcnt vmcnt(8)
	s_waitcnt lgkmcnt(0)
	s_barrier
	s_setprio 1
	s_waitcnt lgkmcnt(0)
	v_mfma_f32_16x16x32_bf16 v[130:133], v[210:213], v[134:137], v[130:133]
	v_mfma_f32_16x16x32_bf16 v[126:129], v[210:213], v[162:165], v[126:129]
	v_mfma_f32_16x16x32_bf16 v[122:125], v[218:221], v[134:137], v[122:125]
	v_mfma_f32_16x16x32_bf16 v[118:121], v[218:221], v[162:165], v[118:121]
	v_mfma_f32_16x16x32_bf16 v[114:117], v[226:229], v[134:137], v[114:117]
	v_mfma_f32_16x16x32_bf16 v[110:113], v[226:229], v[162:165], v[110:113]
	v_mfma_f32_16x16x32_bf16 v[106:109], v[234:237], v[134:137], v[106:109]
	v_mfma_f32_16x16x32_bf16 v[102:105], v[234:237], v[162:165], v[102:105]
	v_mfma_f32_16x16x32_bf16 v[130:133], v[214:217], v[138:141], v[130:133]
	v_mfma_f32_16x16x32_bf16 v[126:129], v[214:217], v[166:169], v[126:129]
	v_mfma_f32_16x16x32_bf16 v[122:125], v[222:225], v[138:141], v[122:125]
	v_mfma_f32_16x16x32_bf16 v[118:121], v[222:225], v[166:169], v[118:121]
	v_mfma_f32_16x16x32_bf16 v[114:117], v[230:233], v[138:141], v[114:117]
	v_mfma_f32_16x16x32_bf16 v[110:113], v[230:233], v[166:169], v[110:113]
	v_mfma_f32_16x16x32_bf16 v[106:109], v[238:241], v[138:141], v[106:109]
	v_mfma_f32_16x16x32_bf16 v[102:105], v[238:241], v[166:169], v[102:105]
	s_setprio 0
	s_setprio 1
	v_mfma_f32_16x16x32_bf16 v[64:67], v[170:173], v[210:213], v[64:67]
	v_mfma_f32_16x16x32_bf16 v[60:63], v[178:181], v[210:213], v[60:63]
	v_mfma_f32_16x16x32_bf16 v[56:59], v[170:173], v[218:221], v[56:59]
	v_mfma_f32_16x16x32_bf16 v[52:55], v[178:181], v[218:221], v[52:55]
	v_mfma_f32_16x16x32_bf16 v[48:51], v[170:173], v[226:229], v[48:51]
	v_mfma_f32_16x16x32_bf16 v[44:47], v[178:181], v[226:229], v[44:47]
	v_mfma_f32_16x16x32_bf16 v[40:43], v[170:173], v[234:237], v[40:43]
	v_mfma_f32_16x16x32_bf16 v[36:39], v[178:181], v[234:237], v[36:39]
	v_mfma_f32_16x16x32_bf16 v[64:67], v[174:177], v[214:217], v[64:67]
	v_mfma_f32_16x16x32_bf16 v[60:63], v[206:209], v[214:217], v[60:63]
	v_mfma_f32_16x16x32_bf16 v[56:59], v[174:177], v[222:225], v[56:59]
	v_mfma_f32_16x16x32_bf16 v[52:55], v[206:209], v[222:225], v[52:55]
	v_mfma_f32_16x16x32_bf16 v[48:51], v[174:177], v[230:233], v[48:51]
	v_mfma_f32_16x16x32_bf16 v[44:47], v[206:209], v[230:233], v[44:47]
	v_mfma_f32_16x16x32_bf16 v[40:43], v[174:177], v[238:241], v[40:43]
	v_mfma_f32_16x16x32_bf16 v[36:39], v[206:209], v[238:241], v[36:39]
	s_setprio 0
	s_barrier
	s_add_i32 s84, s75, s3
	s_mov_b32 m0, s84
	ds_read_b128 v[210:213], v202 offset:16384
	ds_read_b128 v[214:217], v202 offset:17408
	ds_read_b128 v[218:221], v202 offset:18432
	ds_read_b128 v[222:225], v202 offset:19456
	ds_read_b128 v[226:229], v202 offset:20480
	ds_read_b128 v[230:233], v202 offset:21504
	ds_read_b128 v[234:237], v202 offset:22528
	ds_read_b128 v[238:241], v202 offset:23552
	global_load_lds_dwordx4 v144, s[62:63]
	s_add_i32 m0, s84, 0x2000
	s_add_u32 s84, s62, 0x100000
	s_addc_u32 s85, s63, 0
	s_add_i32 s86, s80, s3
	global_load_lds_dwordx4 v148, s[62:63]
	s_mov_b32 m0, s86
	s_nop 0
	global_load_lds_dwordx4 v144, s[84:85]
	s_add_i32 m0, s86, 0x2000
	s_nop 0
	global_load_lds_dwordx4 v148, s[84:85]
	s_mov_b32 m0, s39
	s_nop 0
	global_load_lds_dwordx4 v142, s[78:79]
	s_mov_b32 m0, s54
	s_nop 0
	global_load_lds_dwordx4 v146, s[78:79]
	s_waitcnt vmcnt(8)
	s_waitcnt lgkmcnt(0)
	s_barrier
	s_setprio 1
	s_waitcnt lgkmcnt(0)
	v_mfma_f32_16x16x32_bf16 v[98:101], v[210:213], v[134:137], v[98:101]
	v_mfma_f32_16x16x32_bf16 v[94:97], v[210:213], v[162:165], v[94:97]
	v_mfma_f32_16x16x32_bf16 v[90:93], v[218:221], v[134:137], v[90:93]
	v_mfma_f32_16x16x32_bf16 v[86:89], v[218:221], v[162:165], v[86:89]
	v_mfma_f32_16x16x32_bf16 v[82:85], v[226:229], v[134:137], v[82:85]
	v_mfma_f32_16x16x32_bf16 v[68:71], v[226:229], v[162:165], v[68:71]
	v_mfma_f32_16x16x32_bf16 v[72:75], v[234:237], v[134:137], v[74:77]
	v_mfma_f32_16x16x32_bf16 v[76:79], v[234:237], v[162:165], v[78:81]
	v_mfma_f32_16x16x32_bf16 v[98:101], v[214:217], v[138:141], v[98:101]
	v_mfma_f32_16x16x32_bf16 v[94:97], v[214:217], v[166:169], v[94:97]
	v_mfma_f32_16x16x32_bf16 v[90:93], v[222:225], v[138:141], v[90:93]
	v_mfma_f32_16x16x32_bf16 v[86:89], v[222:225], v[166:169], v[86:89]
	v_mfma_f32_16x16x32_bf16 v[82:85], v[230:233], v[138:141], v[82:85]
	v_mfma_f32_16x16x32_bf16 v[68:71], v[230:233], v[166:169], v[68:71]
	v_mfma_f32_16x16x32_bf16 v[72:75], v[238:241], v[138:141], v[72:75]
	v_mfma_f32_16x16x32_bf16 v[78:81], v[238:241], v[166:169], v[76:79]
	s_setprio 0
	s_setprio 1
	v_mfma_f32_16x16x32_bf16 v[32:35], v[170:173], v[210:213], v[32:35]
	v_mfma_f32_16x16x32_bf16 v[28:31], v[178:181], v[210:213], v[28:31]
	v_mfma_f32_16x16x32_bf16 v[24:27], v[170:173], v[218:221], v[24:27]
	v_mfma_f32_16x16x32_bf16 v[20:23], v[178:181], v[218:221], v[20:23]
	v_mfma_f32_16x16x32_bf16 v[16:19], v[170:173], v[226:229], v[16:19]
	v_mfma_f32_16x16x32_bf16 v[12:15], v[178:181], v[226:229], v[12:15]
	v_mfma_f32_16x16x32_bf16 v[2:5], v[170:173], v[234:237], v[4:7]
	v_mfma_f32_16x16x32_bf16 v[6:9], v[178:181], v[234:237], v[8:11]
	v_mfma_f32_16x16x32_bf16 v[32:35], v[174:177], v[214:217], v[32:35]
	v_mfma_f32_16x16x32_bf16 v[28:31], v[206:209], v[214:217], v[28:31]
	v_mfma_f32_16x16x32_bf16 v[24:27], v[174:177], v[222:225], v[24:27]
	v_mfma_f32_16x16x32_bf16 v[20:23], v[206:209], v[222:225], v[20:23]
	v_mfma_f32_16x16x32_bf16 v[16:19], v[174:177], v[230:233], v[16:19]
	v_mfma_f32_16x16x32_bf16 v[12:15], v[206:209], v[230:233], v[12:15]
	v_mfma_f32_16x16x32_bf16 v[2:5], v[174:177], v[238:241], v[2:5]
	v_mfma_f32_16x16x32_bf16 v[8:11], v[206:209], v[238:241], v[6:9]
	s_setprio 0
	s_barrier
	s_add_i32 s84, 0, 0x18000
	v_add_u32_e32 v1, s84, v183
	s_add_i32 s85, 0, 0x1c000
	ds_read_b128 v[134:137], v1
	ds_read_b128 v[138:141], v1 offset:1024
	ds_read_b128 v[162:165], v1 offset:2048
	ds_read_b128 v[166:169], v1 offset:3072
	v_add_u32_e32 v1, s85, v183
	ds_read_b128 v[170:173], v1
	ds_read_b128 v[174:177], v1 offset:1024
	ds_read_b128 v[178:181], v1 offset:2048
	ds_read_b128 v[206:209], v1 offset:3072
	s_add_u32 s78, s78, 0x100000
	s_addc_u32 s79, s79, 0
	s_mov_b32 m0, s55
	ds_read_b128 v[210:213], v202 offset:32768
	ds_read_b128 v[214:217], v202 offset:33792
	ds_read_b128 v[218:221], v202 offset:34816
	ds_read_b128 v[222:225], v202 offset:35840
	ds_read_b128 v[226:229], v202 offset:36864
	ds_read_b128 v[230:233], v202 offset:37888
	ds_read_b128 v[234:237], v202 offset:38912
	ds_read_b128 v[238:241], v202 offset:39936
	global_load_lds_dwordx4 v142, s[78:79]
	s_mov_b32 m0, s68
	s_nop 0
	global_load_lds_dwordx4 v146, s[78:79]
	s_waitcnt vmcnt(8)
	s_waitcnt lgkmcnt(0)
	s_barrier
	s_setprio 1
	s_waitcnt lgkmcnt(0)
	v_mfma_f32_16x16x32_bf16 v[130:133], v[210:213], v[134:137], v[130:133]
	v_mfma_f32_16x16x32_bf16 v[126:129], v[210:213], v[162:165], v[126:129]
	v_mfma_f32_16x16x32_bf16 v[122:125], v[218:221], v[134:137], v[122:125]
	v_mfma_f32_16x16x32_bf16 v[118:121], v[218:221], v[162:165], v[118:121]
	v_mfma_f32_16x16x32_bf16 v[114:117], v[226:229], v[134:137], v[114:117]
	v_mfma_f32_16x16x32_bf16 v[110:113], v[226:229], v[162:165], v[110:113]
	v_mfma_f32_16x16x32_bf16 v[106:109], v[234:237], v[134:137], v[106:109]
	v_mfma_f32_16x16x32_bf16 v[102:105], v[234:237], v[162:165], v[102:105]
	v_mfma_f32_16x16x32_bf16 v[130:133], v[214:217], v[138:141], v[130:133]
	v_mfma_f32_16x16x32_bf16 v[126:129], v[214:217], v[166:169], v[126:129]
	v_mfma_f32_16x16x32_bf16 v[122:125], v[222:225], v[138:141], v[122:125]
	v_mfma_f32_16x16x32_bf16 v[118:121], v[222:225], v[166:169], v[118:121]
	v_mfma_f32_16x16x32_bf16 v[114:117], v[230:233], v[138:141], v[114:117]
	v_mfma_f32_16x16x32_bf16 v[110:113], v[230:233], v[166:169], v[110:113]
	v_mfma_f32_16x16x32_bf16 v[106:109], v[238:241], v[138:141], v[106:109]
	v_mfma_f32_16x16x32_bf16 v[102:105], v[238:241], v[166:169], v[102:105]
	s_setprio 0
	s_setprio 1
	v_mfma_f32_16x16x32_bf16 v[64:67], v[170:173], v[210:213], v[64:67]
	v_mfma_f32_16x16x32_bf16 v[60:63], v[178:181], v[210:213], v[60:63]
	v_mfma_f32_16x16x32_bf16 v[56:59], v[170:173], v[218:221], v[56:59]
	v_mfma_f32_16x16x32_bf16 v[52:55], v[178:181], v[218:221], v[52:55]
	v_mfma_f32_16x16x32_bf16 v[48:51], v[170:173], v[226:229], v[48:51]
	v_mfma_f32_16x16x32_bf16 v[44:47], v[178:181], v[226:229], v[44:47]
	v_mfma_f32_16x16x32_bf16 v[40:43], v[170:173], v[234:237], v[40:43]
	v_mfma_f32_16x16x32_bf16 v[36:39], v[178:181], v[234:237], v[36:39]
	v_mfma_f32_16x16x32_bf16 v[64:67], v[174:177], v[214:217], v[64:67]
	v_mfma_f32_16x16x32_bf16 v[60:63], v[206:209], v[214:217], v[60:63]
	v_mfma_f32_16x16x32_bf16 v[56:59], v[174:177], v[222:225], v[56:59]
	v_mfma_f32_16x16x32_bf16 v[52:55], v[206:209], v[222:225], v[52:55]
	v_mfma_f32_16x16x32_bf16 v[48:51], v[174:177], v[230:233], v[48:51]
	v_mfma_f32_16x16x32_bf16 v[44:47], v[206:209], v[230:233], v[44:47]
	v_mfma_f32_16x16x32_bf16 v[40:43], v[174:177], v[238:241], v[40:43]
	v_mfma_f32_16x16x32_bf16 v[36:39], v[206:209], v[238:241], v[36:39]
	s_setprio 0
	s_barrier
	s_add_i32 s78, s84, s3
	s_mov_b32 m0, s78
	ds_read_b128 v[210:213], v202 offset:49152
	ds_read_b128 v[214:217], v202 offset:50176
	ds_read_b128 v[218:221], v202 offset:51200
	ds_read_b128 v[222:225], v202 offset:52224
	ds_read_b128 v[226:229], v202 offset:53248
	ds_read_b128 v[230:233], v202 offset:54272
	ds_read_b128 v[234:237], v202 offset:55296
	ds_read_b128 v[238:241], v202 offset:56320
	global_load_lds_dwordx4 v144, s[98:99]
	s_add_i32 m0, s78, 0x2000
	s_add_u32 s62, s62, 0x100080
	s_addc_u32 s63, s63, 0
	s_add_i32 s78, s85, s3
	global_load_lds_dwordx4 v148, s[98:99]
	s_mov_b32 m0, s78
	s_nop 0
	global_load_lds_dwordx4 v144, s[62:63]
	s_add_i32 m0, s78, 0x2000
	s_nop 0
	global_load_lds_dwordx4 v148, s[62:63]
	s_mov_b32 m0, s71
	s_nop 0
	global_load_lds_dwordx4 v142, s[100:101]
	s_mov_b32 m0, s72
	s_nop 0
	global_load_lds_dwordx4 v146, s[100:101]
	s_waitcnt vmcnt(8)
	s_waitcnt lgkmcnt(0)
	s_barrier
	s_setprio 1
	s_waitcnt lgkmcnt(0)
	v_mfma_f32_16x16x32_bf16 v[98:101], v[210:213], v[134:137], v[98:101]
	v_mfma_f32_16x16x32_bf16 v[94:97], v[210:213], v[162:165], v[94:97]
	v_mfma_f32_16x16x32_bf16 v[90:93], v[218:221], v[134:137], v[90:93]
	v_mfma_f32_16x16x32_bf16 v[86:89], v[218:221], v[162:165], v[86:89]
	v_mfma_f32_16x16x32_bf16 v[82:85], v[226:229], v[134:137], v[82:85]
	v_mfma_f32_16x16x32_bf16 v[68:71], v[226:229], v[162:165], v[68:71]
	v_mfma_f32_16x16x32_bf16 v[72:75], v[234:237], v[134:137], v[72:75]
	v_mfma_f32_16x16x32_bf16 v[78:81], v[234:237], v[162:165], v[78:81]
	v_mfma_f32_16x16x32_bf16 v[98:101], v[214:217], v[138:141], v[98:101]
	v_mfma_f32_16x16x32_bf16 v[94:97], v[214:217], v[166:169], v[94:97]
	v_mfma_f32_16x16x32_bf16 v[90:93], v[222:225], v[138:141], v[90:93]
	v_mfma_f32_16x16x32_bf16 v[86:89], v[222:225], v[166:169], v[86:89]
	v_mfma_f32_16x16x32_bf16 v[82:85], v[230:233], v[138:141], v[82:85]
	v_mfma_f32_16x16x32_bf16 v[68:71], v[230:233], v[166:169], v[68:71]
	v_mfma_f32_16x16x32_bf16 v[74:77], v[238:241], v[138:141], v[72:75]
	v_mfma_f32_16x16x32_bf16 v[78:81], v[238:241], v[166:169], v[78:81]
	s_setprio 0
	s_setprio 1
	v_mfma_f32_16x16x32_bf16 v[32:35], v[170:173], v[210:213], v[32:35]
	v_mfma_f32_16x16x32_bf16 v[28:31], v[178:181], v[210:213], v[28:31]
	v_mfma_f32_16x16x32_bf16 v[24:27], v[170:173], v[218:221], v[24:27]
	v_mfma_f32_16x16x32_bf16 v[20:23], v[178:181], v[218:221], v[20:23]
	v_mfma_f32_16x16x32_bf16 v[16:19], v[170:173], v[226:229], v[16:19]
	v_mfma_f32_16x16x32_bf16 v[12:15], v[178:181], v[226:229], v[12:15]
	v_mfma_f32_16x16x32_bf16 v[2:5], v[170:173], v[234:237], v[2:5]
	v_mfma_f32_16x16x32_bf16 v[8:11], v[178:181], v[234:237], v[8:11]
	v_mfma_f32_16x16x32_bf16 v[32:35], v[174:177], v[214:217], v[32:35]
	v_mfma_f32_16x16x32_bf16 v[28:31], v[206:209], v[214:217], v[28:31]
	v_mfma_f32_16x16x32_bf16 v[24:27], v[174:177], v[222:225], v[24:27]
	v_mfma_f32_16x16x32_bf16 v[20:23], v[206:209], v[222:225], v[20:23]
	v_mfma_f32_16x16x32_bf16 v[16:19], v[174:177], v[230:233], v[16:19]
	v_mfma_f32_16x16x32_bf16 v[12:15], v[206:209], v[230:233], v[12:15]
	v_mfma_f32_16x16x32_bf16 v[4:7], v[174:177], v[238:241], v[2:5]
	v_mfma_f32_16x16x32_bf16 v[8:11], v[206:209], v[238:241], v[8:11]
	s_setprio 0
	s_barrier
	s_add_i32 s83, s83, 2
	s_add_u32 s20, s20, 0x100
	s_addc_u32 s21, s21, 0
	s_add_u32 s81, s81, 0x100
	s_addc_u32 s82, s82, 0
	s_cmp_gt_u32 s83, 61
	s_cbranch_scc0 .LBB0_528
	s_and_b64 vcc, exec, s[34:35]
	s_cbranch_vccz .LBB0_531
	s_barrier

.LBB0_815:
	ds_read_b128 v[56:59], v241
	ds_read_b128 v[60:63], v241 offset:1024
	ds_read_b128 v[64:67], v241 offset:2048
	ds_read_b128 v[68:71], v241 offset:3072
	ds_read_b128 v[144:147], v242
	ds_read_b128 v[148:151], v242 offset:1024
	ds_read_b128 v[152:155], v242 offset:2048
	ds_read_b128 v[156:159], v242 offset:3072
	s_add_u32 s50, s46, 0xffe00080
	s_addc_u32 s51, s47, -1
	s_cmpk_eq_i32 s77, 0x7c
	s_cselect_b32 s53, s29, s51
	s_cselect_b32 s52, s39, s50
	s_cselect_b32 s51, s31, s76
	s_cselect_b32 s50, s41, s75
	s_add_u32 s98, s50, s12
	s_addc_u32 s99, s51, s13
	s_add_u32 s100, s52, s12
	s_addc_u32 s101, s53, s13
	s_add_i32 m0, s55, 0xc000
	ds_read_b128 v[160:163], v243
	ds_read_b128 v[164:167], v243 offset:1024
	ds_read_b128 v[168:171], v243 offset:2048
	ds_read_b128 v[172:175], v243 offset:3072
	ds_read_b128 v[176:179], v243 offset:4096
	ds_read_b128 v[180:183], v243 offset:5120
	ds_read_b128 v[184:187], v243 offset:6144
	ds_read_b128 v[188:191], v243 offset:7168
	global_load_lds_dwordx4 v216, s[46:47]
	s_add_i32 m0, s55, 0xe000
	s_nop 0
	global_load_lds_dwordx4 v218, s[46:47]
	s_waitcnt vmcnt(8)
	s_waitcnt lgkmcnt(0)
	s_barrier
	s_setprio 1
	s_waitcnt lgkmcnt(0)
	v_mfma_f32_16x16x32_bf16 v[140:143], v[56:59], v[160:163], v[140:143]
	v_mfma_f32_16x16x32_bf16 v[136:139], v[64:67], v[160:163], v[136:139]
	v_mfma_f32_16x16x32_bf16 v[124:127], v[56:59], v[168:171], v[124:127]
	v_mfma_f32_16x16x32_bf16 v[120:123], v[64:67], v[168:171], v[120:123]
	v_mfma_f32_16x16x32_bf16 v[108:111], v[56:59], v[176:179], v[108:111]
	v_mfma_f32_16x16x32_bf16 v[104:107], v[64:67], v[176:179], v[104:107]
	v_mfma_f32_16x16x32_bf16 v[92:95], v[56:59], v[184:187], v[92:95]
	v_mfma_f32_16x16x32_bf16 v[88:91], v[64:67], v[184:187], v[88:91]
	v_mfma_f32_16x16x32_bf16 v[140:143], v[60:63], v[164:167], v[140:143]
	v_mfma_f32_16x16x32_bf16 v[136:139], v[68:71], v[164:167], v[136:139]
	v_mfma_f32_16x16x32_bf16 v[124:127], v[60:63], v[172:175], v[124:127]
	v_mfma_f32_16x16x32_bf16 v[120:123], v[68:71], v[172:175], v[120:123]
	v_mfma_f32_16x16x32_bf16 v[108:111], v[60:63], v[180:183], v[108:111]
	v_mfma_f32_16x16x32_bf16 v[104:107], v[68:71], v[180:183], v[104:107]
	v_mfma_f32_16x16x32_bf16 v[92:95], v[60:63], v[188:191], v[92:95]
	v_mfma_f32_16x16x32_bf16 v[88:91], v[68:71], v[188:191], v[88:91]
	s_setprio 0
	s_setprio 1
	v_mfma_f32_16x16x32_bf16 v[132:135], v[144:147], v[160:163], v[132:135]
	v_mfma_f32_16x16x32_bf16 v[128:131], v[152:155], v[160:163], v[128:131]
	v_mfma_f32_16x16x32_bf16 v[116:119], v[144:147], v[168:171], v[116:119]
	v_mfma_f32_16x16x32_bf16 v[112:115], v[152:155], v[168:171], v[112:115]
	v_mfma_f32_16x16x32_bf16 v[100:103], v[144:147], v[176:179], v[100:103]
	v_mfma_f32_16x16x32_bf16 v[96:99], v[152:155], v[176:179], v[96:99]
	v_mfma_f32_16x16x32_bf16 v[84:87], v[144:147], v[184:187], v[84:87]
	v_mfma_f32_16x16x32_bf16 v[80:83], v[152:155], v[184:187], v[80:83]
	v_mfma_f32_16x16x32_bf16 v[132:135], v[148:151], v[164:167], v[132:135]
	v_mfma_f32_16x16x32_bf16 v[128:131], v[156:159], v[164:167], v[128:131]
	v_mfma_f32_16x16x32_bf16 v[116:119], v[148:151], v[172:175], v[116:119]
	v_mfma_f32_16x16x32_bf16 v[112:115], v[156:159], v[172:175], v[112:115]
	v_mfma_f32_16x16x32_bf16 v[100:103], v[148:151], v[180:183], v[100:103]
	v_mfma_f32_16x16x32_bf16 v[96:99], v[156:159], v[180:183], v[96:99]
	v_mfma_f32_16x16x32_bf16 v[84:87], v[148:151], v[188:191], v[84:87]
	v_mfma_f32_16x16x32_bf16 v[80:83], v[156:159], v[188:191], v[80:83]
	s_setprio 0
	s_barrier
	s_add_i32 s78, s73, s54
	s_mov_b32 m0, s78
	ds_read_b128 v[160:163], v243 offset:16384
	ds_read_b128 v[164:167], v243 offset:17408
	ds_read_b128 v[168:171], v243 offset:18432
	ds_read_b128 v[172:175], v243 offset:19456
	ds_read_b128 v[176:179], v243 offset:20480
	ds_read_b128 v[180:183], v243 offset:21504
	ds_read_b128 v[184:187], v243 offset:22528
	ds_read_b128 v[188:191], v243 offset:23552
	global_load_lds_dwordx4 v210, s[50:51]
	s_add_i32 m0, s78, 0x2000
	s_add_u32 s78, s50, 0x200000
	s_addc_u32 s79, s51, 0
	s_add_i32 s80, s74, s54
	global_load_lds_dwordx4 v214, s[50:51]
	s_mov_b32 m0, s80
	s_nop 0
	global_load_lds_dwordx4 v210, s[78:79]
	s_add_i32 m0, s80, 0x2000
	s_nop 0
	global_load_lds_dwordx4 v214, s[78:79]
	s_mov_b32 m0, s55
	s_nop 0
	global_load_lds_dwordx4 v208, s[52:53]
	s_mov_b32 m0, s56
	s_nop 0
	global_load_lds_dwordx4 v212, s[52:53]
	s_waitcnt vmcnt(8)
	s_waitcnt lgkmcnt(0)
	s_barrier
	s_setprio 1
	s_waitcnt lgkmcnt(0)
	v_mfma_f32_16x16x32_bf16 v[76:79], v[56:59], v[160:163], v[76:79]
	v_mfma_f32_16x16x32_bf16 v[72:75], v[64:67], v[160:163], v[72:75]
	v_mfma_f32_16x16x32_bf16 v[44:47], v[56:59], v[168:171], v[44:47]
	v_mfma_f32_16x16x32_bf16 v[40:43], v[64:67], v[168:171], v[40:43]
	v_mfma_f32_16x16x32_bf16 v[28:31], v[56:59], v[176:179], v[28:31]
	v_mfma_f32_16x16x32_bf16 v[24:27], v[64:67], v[176:179], v[24:27]
	v_mfma_f32_16x16x32_bf16 v[12:15], v[56:59], v[184:187], v[12:15]
	v_mfma_f32_16x16x32_bf16 v[8:11], v[64:67], v[184:187], v[8:11]
	v_mfma_f32_16x16x32_bf16 v[76:79], v[60:63], v[164:167], v[76:79]
	v_mfma_f32_16x16x32_bf16 v[72:75], v[68:71], v[164:167], v[72:75]
	v_mfma_f32_16x16x32_bf16 v[44:47], v[60:63], v[172:175], v[44:47]
	v_mfma_f32_16x16x32_bf16 v[40:43], v[68:71], v[172:175], v[40:43]
	v_mfma_f32_16x16x32_bf16 v[28:31], v[60:63], v[180:183], v[28:31]
	v_mfma_f32_16x16x32_bf16 v[24:27], v[68:71], v[180:183], v[24:27]
	v_mfma_f32_16x16x32_bf16 v[12:15], v[60:63], v[188:191], v[12:15]
	v_mfma_f32_16x16x32_bf16 v[8:11], v[68:71], v[188:191], v[8:11]
	s_setprio 0
	s_setprio 1
	v_mfma_f32_16x16x32_bf16 v[52:55], v[144:147], v[160:163], v[52:55]
	v_mfma_f32_16x16x32_bf16 v[48:51], v[152:155], v[160:163], v[48:51]
	v_mfma_f32_16x16x32_bf16 v[36:39], v[144:147], v[168:171], v[36:39]
	v_mfma_f32_16x16x32_bf16 v[32:35], v[152:155], v[168:171], v[32:35]
	v_mfma_f32_16x16x32_bf16 v[20:23], v[144:147], v[176:179], v[20:23]
	v_mfma_f32_16x16x32_bf16 v[16:19], v[152:155], v[176:179], v[16:19]
	v_mfma_f32_16x16x32_bf16 v[4:7], v[144:147], v[184:187], v[4:7]
	v_mfma_f32_16x16x32_bf16 v[0:3], v[152:155], v[184:187], v[0:3]
	v_mfma_f32_16x16x32_bf16 v[52:55], v[148:151], v[164:167], v[52:55]
	v_mfma_f32_16x16x32_bf16 v[48:51], v[156:159], v[164:167], v[48:51]
	v_mfma_f32_16x16x32_bf16 v[36:39], v[148:151], v[172:175], v[36:39]
	v_mfma_f32_16x16x32_bf16 v[32:35], v[156:159], v[172:175], v[32:35]
	v_mfma_f32_16x16x32_bf16 v[20:23], v[148:151], v[180:183], v[20:23]
	v_mfma_f32_16x16x32_bf16 v[16:19], v[156:159], v[180:183], v[16:19]
	v_mfma_f32_16x16x32_bf16 v[4:7], v[148:151], v[188:191], v[4:7]
	v_mfma_f32_16x16x32_bf16 v[0:3], v[156:159], v[188:191], v[0:3]
	s_setprio 0
	s_barrier
	s_add_i32 s78, 0, 0x18000
	s_add_i32 s79, 0, 0x1c000
	v_add_u32_e32 v68, s78, v239
	v_add_u32_e32 v156, s79, v239
	ds_read_b128 v[56:59], v68
	ds_read_b128 v[60:63], v68 offset:1024
	ds_read_b128 v[64:67], v68 offset:2048
	ds_read_b128 v[68:71], v68 offset:3072
	ds_read_b128 v[144:147], v156
	ds_read_b128 v[148:151], v156 offset:1024
	ds_read_b128 v[152:155], v156 offset:2048
	ds_read_b128 v[156:159], v156 offset:3072
	s_add_u32 s52, s52, 0x200000
	s_addc_u32 s53, s53, 0
	s_mov_b32 m0, s57
	ds_read_b128 v[160:163], v243 offset:32768
	ds_read_b128 v[164:167], v243 offset:33792
	ds_read_b128 v[168:171], v243 offset:34816
	ds_read_b128 v[172:175], v243 offset:35840
	ds_read_b128 v[176:179], v243 offset:36864
	ds_read_b128 v[180:183], v243 offset:37888
	ds_read_b128 v[184:187], v243 offset:38912
	ds_read_b128 v[188:191], v243 offset:39936
	global_load_lds_dwordx4 v208, s[52:53]
	s_mov_b32 m0, s58
	s_nop 0
	global_load_lds_dwordx4 v212, s[52:53]
	s_waitcnt vmcnt(8)
	s_waitcnt lgkmcnt(0)
	s_barrier
	s_setprio 1
	s_waitcnt lgkmcnt(0)
	v_mfma_f32_16x16x32_bf16 v[140:143], v[56:59], v[160:163], v[140:143]
	v_mfma_f32_16x16x32_bf16 v[136:139], v[64:67], v[160:163], v[136:139]
	v_mfma_f32_16x16x32_bf16 v[124:127], v[56:59], v[168:171], v[124:127]
	v_mfma_f32_16x16x32_bf16 v[120:123], v[64:67], v[168:171], v[120:123]
	v_mfma_f32_16x16x32_bf16 v[108:111], v[56:59], v[176:179], v[108:111]
	v_mfma_f32_16x16x32_bf16 v[104:107], v[64:67], v[176:179], v[104:107]
	v_mfma_f32_16x16x32_bf16 v[92:95], v[56:59], v[184:187], v[92:95]
	v_mfma_f32_16x16x32_bf16 v[88:91], v[64:67], v[184:187], v[88:91]
	v_mfma_f32_16x16x32_bf16 v[140:143], v[60:63], v[164:167], v[140:143]
	v_mfma_f32_16x16x32_bf16 v[136:139], v[68:71], v[164:167], v[136:139]
	v_mfma_f32_16x16x32_bf16 v[124:127], v[60:63], v[172:175], v[124:127]
	v_mfma_f32_16x16x32_bf16 v[120:123], v[68:71], v[172:175], v[120:123]
	v_mfma_f32_16x16x32_bf16 v[108:111], v[60:63], v[180:183], v[108:111]
	v_mfma_f32_16x16x32_bf16 v[104:107], v[68:71], v[180:183], v[104:107]
	v_mfma_f32_16x16x32_bf16 v[92:95], v[60:63], v[188:191], v[92:95]
	v_mfma_f32_16x16x32_bf16 v[88:91], v[68:71], v[188:191], v[88:91]
	s_setprio 0
	s_setprio 1
	v_mfma_f32_16x16x32_bf16 v[132:135], v[144:147], v[160:163], v[132:135]
	v_mfma_f32_16x16x32_bf16 v[128:131], v[152:155], v[160:163], v[128:131]
	v_mfma_f32_16x16x32_bf16 v[116:119], v[144:147], v[168:171], v[116:119]
	v_mfma_f32_16x16x32_bf16 v[112:115], v[152:155], v[168:171], v[112:115]
	v_mfma_f32_16x16x32_bf16 v[100:103], v[144:147], v[176:179], v[100:103]
	v_mfma_f32_16x16x32_bf16 v[96:99], v[152:155], v[176:179], v[96:99]
	v_mfma_f32_16x16x32_bf16 v[84:87], v[144:147], v[184:187], v[84:87]
	v_mfma_f32_16x16x32_bf16 v[80:83], v[152:155], v[184:187], v[80:83]
	v_mfma_f32_16x16x32_bf16 v[132:135], v[148:151], v[164:167], v[132:135]
	v_mfma_f32_16x16x32_bf16 v[128:131], v[156:159], v[164:167], v[128:131]
	v_mfma_f32_16x16x32_bf16 v[116:119], v[148:151], v[172:175], v[116:119]
	v_mfma_f32_16x16x32_bf16 v[112:115], v[156:159], v[172:175], v[112:115]
	v_mfma_f32_16x16x32_bf16 v[100:103], v[148:151], v[180:183], v[100:103]
	v_mfma_f32_16x16x32_bf16 v[96:99], v[156:159], v[180:183], v[96:99]
	v_mfma_f32_16x16x32_bf16 v[84:87], v[148:151], v[188:191], v[84:87]
	v_mfma_f32_16x16x32_bf16 v[80:83], v[156:159], v[188:191], v[80:83]
	s_setprio 0
	s_barrier
	s_add_i32 s52, s78, s54
	s_mov_b32 m0, s52
	ds_read_b128 v[160:163], v243 offset:49152
	ds_read_b128 v[164:167], v243 offset:50176
	ds_read_b128 v[168:171], v243 offset:51200
	ds_read_b128 v[172:175], v243 offset:52224
	ds_read_b128 v[176:179], v243 offset:53248
	ds_read_b128 v[180:183], v243 offset:54272
	ds_read_b128 v[184:187], v243 offset:55296
	ds_read_b128 v[188:191], v243 offset:56320
	global_load_lds_dwordx4 v210, s[98:99]
	s_add_i32 m0, s52, 0x2000
	s_add_u32 s50, s50, 0x200080
	s_addc_u32 s51, s51, 0
	s_add_i32 s52, s79, s54
	global_load_lds_dwordx4 v214, s[98:99]
	s_mov_b32 m0, s52
	s_nop 0
	global_load_lds_dwordx4 v210, s[50:51]
	s_add_i32 m0, s52, 0x2000
	s_nop 0
	global_load_lds_dwordx4 v214, s[50:51]
	s_mov_b32 m0, s63
	s_nop 0
	global_load_lds_dwordx4 v208, s[100:101]
	s_mov_b32 m0, s68
	s_nop 0
	global_load_lds_dwordx4 v212, s[100:101]
	s_waitcnt vmcnt(8)
	s_waitcnt lgkmcnt(0)
	s_barrier
	s_setprio 1
	s_waitcnt lgkmcnt(0)
	v_mfma_f32_16x16x32_bf16 v[76:79], v[56:59], v[160:163], v[76:79]
	v_mfma_f32_16x16x32_bf16 v[72:75], v[64:67], v[160:163], v[72:75]
	v_mfma_f32_16x16x32_bf16 v[44:47], v[56:59], v[168:171], v[44:47]
	v_mfma_f32_16x16x32_bf16 v[40:43], v[64:67], v[168:171], v[40:43]
	v_mfma_f32_16x16x32_bf16 v[28:31], v[56:59], v[176:179], v[28:31]
	v_mfma_f32_16x16x32_bf16 v[24:27], v[64:67], v[176:179], v[24:27]
	v_mfma_f32_16x16x32_bf16 v[12:15], v[56:59], v[184:187], v[12:15]
	v_mfma_f32_16x16x32_bf16 v[8:11], v[64:67], v[184:187], v[8:11]
	v_mfma_f32_16x16x32_bf16 v[76:79], v[60:63], v[164:167], v[76:79]
	v_mfma_f32_16x16x32_bf16 v[72:75], v[68:71], v[164:167], v[72:75]
	v_mfma_f32_16x16x32_bf16 v[44:47], v[60:63], v[172:175], v[44:47]
	v_mfma_f32_16x16x32_bf16 v[40:43], v[68:71], v[172:175], v[40:43]
	v_mfma_f32_16x16x32_bf16 v[28:31], v[60:63], v[180:183], v[28:31]
	v_mfma_f32_16x16x32_bf16 v[24:27], v[68:71], v[180:183], v[24:27]
	v_mfma_f32_16x16x32_bf16 v[12:15], v[60:63], v[188:191], v[12:15]
	v_mfma_f32_16x16x32_bf16 v[8:11], v[68:71], v[188:191], v[8:11]
	s_setprio 0
	s_setprio 1
	v_mfma_f32_16x16x32_bf16 v[52:55], v[144:147], v[160:163], v[52:55]
	v_mfma_f32_16x16x32_bf16 v[48:51], v[152:155], v[160:163], v[48:51]
	v_mfma_f32_16x16x32_bf16 v[36:39], v[144:147], v[168:171], v[36:39]
	v_mfma_f32_16x16x32_bf16 v[32:35], v[152:155], v[168:171], v[32:35]
	v_mfma_f32_16x16x32_bf16 v[20:23], v[144:147], v[176:179], v[20:23]
	v_mfma_f32_16x16x32_bf16 v[16:19], v[152:155], v[176:179], v[16:19]
	v_mfma_f32_16x16x32_bf16 v[4:7], v[144:147], v[184:187], v[4:7]
	v_mfma_f32_16x16x32_bf16 v[0:3], v[152:155], v[184:187], v[0:3]
	v_mfma_f32_16x16x32_bf16 v[52:55], v[148:151], v[164:167], v[52:55]
	v_mfma_f32_16x16x32_bf16 v[48:51], v[156:159], v[164:167], v[48:51]
	v_mfma_f32_16x16x32_bf16 v[36:39], v[148:151], v[172:175], v[36:39]
	v_mfma_f32_16x16x32_bf16 v[32:35], v[156:159], v[172:175], v[32:35]
	v_mfma_f32_16x16x32_bf16 v[20:23], v[148:151], v[180:183], v[20:23]
	v_mfma_f32_16x16x32_bf16 v[16:19], v[156:159], v[180:183], v[16:19]
	v_mfma_f32_16x16x32_bf16 v[4:7], v[148:151], v[188:191], v[4:7]
	v_mfma_f32_16x16x32_bf16 v[0:3], v[156:159], v[188:191], v[0:3]
	s_setprio 0
	s_barrier
	s_add_i32 s77, s77, 2
	s_add_u32 s46, s46, 0x100
	s_addc_u32 s47, s47, 0
	s_add_u32 s75, s75, 0x100
	s_addc_u32 s76, s76, 0
	s_cmpk_gt_u32 s77, 0x7d
	s_cbranch_scc0 .LBB0_815
	s_and_b64 vcc, exec, s[14:15]
	s_cbranch_vccz .LBB0_818
	s_barrier
